# GELU epilogue select: 2 v_cmp + 2 v_cndmask + v_pk_mul + v_pk_fma per pair replaced by 2 v_max + 2 v_fma with -|v| source modifiers (bit-identical), 64 pairs per tile epilogue
# speedup vs baseline: 1.0087x; 1.0087x over previous
; #define LAS __attribute__((address_space(3)))
; __device__ __forceinline__ unsigned cvt_pk_bf16(float lo, float hi) { unsigned r; asm volatile("v_cvt_pk_bf16_f32 %0, %1, %2" : "=v"(r) : "v"(lo), "v"(hi)); return r; }
; __device__ __forceinline__ f32x2 gelu_pk(f32x2 v) {
;     const f32x2 av = __builtin_elementwise_abs(v), d = av * 0.2316418882f + 1.0f;
;     f32x2 t; t.x = __builtin_amdgcn_rcpf(d.x); t.y = __builtin_amdgcn_rcpf(d.y);
;     f32x2 q = t * 0.5307027145f + (-0.7265760135f); q = q * t + 0.7107068705f; q = q * t + (-0.142248368f); q = q * t + 0.127414796f; q = q * t;
;     const f32x2 s = (v * v) * (-0.72134752044f);
;     f32x2 e; e.x = __builtin_amdgcn_exp2f(s.x); e.y = __builtin_amdgcn_exp2f(s.y);
;     const f32x2 m = v * (q * e), r = v - m;
;     f32x2 o; o.x = v.x < 0.f ? m.x : r.x; o.y = v.y < 0.f ? m.y : r.y; return o;
;     __device__ __forceinline__ void operator()(const f32x4 (&acc)[2][2][4][2], const Unit& u, int wr, int wc, int fr, int fq) const {
;         const int row0 = u.pm * BM + wr * 64 + fr, col0 = u.pn * BM + wc * 32 + 8 * fq; const bool isv = u.pn >= 4;
;         LAS float* part = (LAS float*)(lds + PART_OFF);
;         float rsv[2][4]; rstd8(ss, row0, rsv);
; #pragma unroll
;         for (int ai = 0; ai < 2; ++ai)
; #pragma unroll
;             for (int m = 0; m < 4; ++m) { const int row = row0 + ai * HALF + m * 16; const float rs = rsv[ai][m]; bf16_t* rowp = O + (size_t)row * ldc + col0; float s1 = 0.f, s2 = 0.f;
; #pragma unroll
;                 for (int bj = 0; bj < 2; ++bj) { f32x4 v0 = acc[ai][bj][m][0] * rs, v1 = acc[ai][bj][m][1] * rs;
;                     const f32x2 a = gelu_pk((f32x2){v0[0], v0[1]}), b = gelu_pk((f32x2){v0[2], v0[3]}), c = gelu_pk((f32x2){v1[0], v1[1]}), d = gelu_pk((f32x2){v1[2], v1[3]});
;                     s1 += ((a.x + a.y) + (b.x + b.y)) + ((c.x + c.y) + (d.x + d.y));
;                     s2 += ((a.x * a.x + a.y * a.y) + (b.x * b.x + b.y * b.y)) + ((c.x * c.x + c.y * c.y) + (d.x * d.x + d.y * d.y));
;                     u32x4 w; w.x = cvt_pk_bf16(a.x, a.y); w.y = cvt_pk_bf16(b.x, b.y); w.z = cvt_pk_bf16(c.x, c.y); w.w = cvt_pk_bf16(d.x, d.y);
;                     *(u32x4*)(rowp + bj * HALF) = w; }
.LBB0_352:
	s_lshl_b32 s27, s10, 8
	v_add_u32_e32 v190, s27, v184
	v_ashrrev_i32_e32 v191, 31, v190
	v_lshl_add_u64 v[34:35], v[190:191], 4, s[22:23]
	global_load_dwordx4 v[176:179], v[34:35], off
	v_or_b32_e32 v174, 16, v190
	v_or_b32_e32 v172, 32, v190
	v_or_b32_e32 v170, 48, v190
	v_add_u32_e32 v168, 0x80, v190
	v_add_u32_e32 v166, 0x90, v190
	v_add_u32_e32 v164, 0xa0, v190
	v_add_u32_e32 v162, 0xb0, v190
	s_mov_b32 s4, 0xbf3a00e3
	v_ashrrev_i32_e32 v175, 31, v174
	v_lshl_add_u64 v[34:35], v[174:175], 4, s[22:23]
	v_ashrrev_i32_e32 v173, 31, v172
	global_load_dwordx4 v[146:149], v[34:35], off
	v_lshl_add_u64 v[34:35], v[172:173], 4, s[22:23]
	v_ashrrev_i32_e32 v171, 31, v170
	global_load_dwordx4 v[126:129], v[34:35], off
	v_lshl_add_u64 v[34:35], v[170:171], 4, s[22:23]
	v_ashrrev_i32_e32 v169, 31, v168
	global_load_dwordx4 v[110:113], v[34:35], off
	v_lshl_add_u64 v[34:35], v[168:169], 4, s[22:23]
	v_ashrrev_i32_e32 v167, 31, v166
	global_load_dwordx4 v[94:97], v[34:35], off
	v_lshl_add_u64 v[34:35], v[166:167], 4, s[22:23]
	v_ashrrev_i32_e32 v165, 31, v164
	global_load_dwordx4 v[74:77], v[34:35], off
	v_lshl_add_u64 v[34:35], v[164:165], 4, s[22:23]
	v_ashrrev_i32_e32 v163, 31, v162
	global_load_dwordx4 v[54:57], v[34:35], off
	v_lshl_add_u64 v[34:35], v[162:163], 4, s[22:23]
	global_load_dwordx4 v[34:37], v[34:35], off
	v_lshl_or_b32 v160, s46, 8, v185
	v_ashrrev_i32_e32 v161, 31, v160
	s_cmp_gt_i32 s46, 3
	s_cselect_b64 s[36:37], -1, 0
	s_cmp_lt_i32 s46, 4
	s_waitcnt vmcnt(0) lgkmcnt(0)
	v_mov_b32_e32 v192, v177
	v_mov_b32_e32 v193, v178
	v_mov_b32_e32 v177, v179
	v_pk_add_f32 v[176:177], v[192:193], v[176:177]
	s_nop 0
	v_add_f32_e32 v0, v176, v177
	v_fmamk_f32 v0, v0, 0x3a800000, v224
	v_rsq_f32_e32 v0, v0
	v_lshlrev_b64 v[176:177], 12, v[190:191]
	v_lshl_add_u64 v[176:177], s[20:21], 0, v[176:177]
	v_lshl_add_u64 v[176:177], v[160:161], 1, v[176:177]
	v_pk_mul_f32 v[178:179], v[154:155], v[0:1] op_sel_hi:[1,0]
	v_pk_mul_f32 v[154:155], v[150:151], v[0:1] op_sel_hi:[1,0]
	v_and_b32_e32 v151, 0x7fffffff, v179
	v_and_b32_e32 v150, 0x7fffffff, v178
	v_pk_fma_f32 v[150:151], v[150:151], s[64:65], 1.0 op_sel_hi:[1,0,0]
	v_pk_mul_f32 v[202:203], v[178:179], v[178:179]
	v_rcp_f32_e32 v190, v150
	v_rcp_f32_e32 v191, v151
	v_mov_b64_e32 v[150:151], s[4:5]
	v_pk_mul_f32 v[202:203], v[202:203], s[76:77] op_sel_hi:[1,0]
	s_nop 0
	v_pk_fma_f32 v[192:193], v[190:191], s[66:67], v[150:151] op_sel_hi:[1,0,0]
	v_exp_f32_e32 v202, v202
	v_pk_fma_f32 v[192:193], v[190:191], v[192:193], s[70:71] op_sel_hi:[1,1,0]
	v_exp_f32_e32 v203, v203
	v_pk_fma_f32 v[192:193], v[190:191], v[192:193], s[72:73] op_sel_hi:[1,1,0]
	v_pk_mul_f32 v[156:157], v[156:157], v[0:1] op_sel_hi:[1,0]
	v_pk_fma_f32 v[192:193], v[190:191], v[192:193], s[74:75] op_sel_hi:[1,1,0]
	v_pk_mul_f32 v[152:153], v[152:153], v[0:1] op_sel_hi:[1,0]
	v_pk_mul_f32 v[190:191], v[190:191], v[192:193]
	v_pk_mul_f32 v[192:193], v[156:157], v[156:157]
	v_pk_mul_f32 v[190:191], v[202:203], v[190:191]
	v_pk_mul_f32 v[192:193], v[192:193], s[76:77] op_sel_hi:[1,0]
	v_max_f32_e32 v202, 0, v178
	v_max_f32_e32 v203, 0, v179
	v_fma_f32 v178, -|v178|, v190, v202
	v_fma_f32 v179, -|v179|, v191, v203
	v_exp_f32_e32 v192, v192
	s_nop 0
	s_nop 0
	v_and_b32_e32 v190, 0x7fffffff, v156
	v_exp_f32_e32 v193, v193
	s_nop 0
	v_and_b32_e32 v191, 0x7fffffff, v157
	v_pk_fma_f32 v[190:191], v[190:191], s[64:65], 1.0 op_sel_hi:[1,0,0]
	s_nop 0
	v_rcp_f32_e32 v190, v190
	v_rcp_f32_e32 v191, v191
	v_pk_mul_f32 v[142:143], v[142:143], v[0:1] op_sel_hi:[1,0]
	v_pk_mul_f32 v[144:145], v[144:145], v[0:1] op_sel_hi:[1,0]
	v_pk_mul_f32 v[140:141], v[140:141], v[0:1] op_sel_hi:[1,0]
	v_pk_fma_f32 v[202:203], v[190:191], s[66:67], v[150:151] op_sel_hi:[1,0,0]
	s_nop 0
	v_pk_fma_f32 v[202:203], v[190:191], v[202:203], s[70:71] op_sel_hi:[1,1,0]
	s_nop 0
	v_pk_fma_f32 v[202:203], v[190:191], v[202:203], s[72:73] op_sel_hi:[1,1,0]
	s_nop 0
	v_pk_fma_f32 v[202:203], v[190:191], v[202:203], s[74:75] op_sel_hi:[1,1,0]
	s_nop 0
	v_pk_mul_f32 v[190:191], v[190:191], v[202:203]
	v_pk_mul_f32 v[202:203], v[154:155], v[154:155]
	v_pk_mul_f32 v[190:191], v[192:193], v[190:191]
	v_pk_mul_f32 v[202:203], v[202:203], s[76:77] op_sel_hi:[1,0]
	v_max_f32_e32 v192, 0, v156
	v_max_f32_e32 v193, 0, v157
	v_fma_f32 v189, -|v156|, v190, v192
	v_fma_f32 v190, -|v157|, v191, v193
	v_and_b32_e32 v156, 0x7fffffff, v154
	s_nop 0
	s_nop 0
	v_and_b32_e32 v157, 0x7fffffff, v155
	v_pk_fma_f32 v[156:157], v[156:157], s[64:65], 1.0 op_sel_hi:[1,0,0]
	s_nop 0
	v_rcp_f32_e32 v156, v156
	v_rcp_f32_e32 v157, v157
	v_exp_f32_e32 v202, v202
	v_exp_f32_e32 v203, v203
	s_nop 0
	v_pk_fma_f32 v[192:193], v[156:157], s[66:67], v[150:151] op_sel_hi:[1,0,0]
	s_nop 0
	v_pk_fma_f32 v[192:193], v[156:157], v[192:193], s[70:71] op_sel_hi:[1,1,0]
	s_nop 0
	v_pk_fma_f32 v[192:193], v[156:157], v[192:193], s[72:73] op_sel_hi:[1,1,0]
	s_nop 0
	v_pk_fma_f32 v[192:193], v[156:157], v[192:193], s[74:75] op_sel_hi:[1,1,0]
	s_nop 0
	v_pk_mul_f32 v[192:193], v[156:157], v[192:193]
	v_pk_mul_f32 v[156:157], v[152:153], v[152:153]
	v_pk_mul_f32 v[192:193], v[202:203], v[192:193]
	v_pk_mul_f32 v[156:157], v[156:157], s[76:77] op_sel_hi:[1,0]
	v_max_f32_e32 v202, 0, v154
	v_max_f32_e32 v203, 0, v155
	v_fma_f32 v154, -|v154|, v192, v202
	v_fma_f32 v155, -|v155|, v193, v203
	v_exp_f32_e32 v156, v156
	s_nop 0
	s_nop 0
	v_and_b32_e32 v192, 0x7fffffff, v152
	v_exp_f32_e32 v157, v157
	s_nop 0
	v_and_b32_e32 v193, 0x7fffffff, v153
	v_pk_fma_f32 v[192:193], v[192:193], s[64:65], 1.0 op_sel_hi:[1,0,0]
	s_nop 0
	v_rcp_f32_e32 v192, v192
	v_rcp_f32_e32 v193, v193
	s_nop 0
; __device__ __forceinline__ unsigned cvt_pk_bf16(float lo, float hi) { unsigned r; asm volatile("v_cvt_pk_bf16_f32 %0, %1, %2" : "=v"(r) : "v"(lo), "v"(hi)); return r; }
; __device__ __forceinline__ f32x2 gelu_pk(f32x2 v) {
;     const f32x2 av = __builtin_elementwise_abs(v), d = av * 0.2316418882f + 1.0f;
;     f32x2 t; t.x = __builtin_amdgcn_rcpf(d.x); t.y = __builtin_amdgcn_rcpf(d.y);
;     f32x2 q = t * 0.5307027145f + (-0.7265760135f); q = q * t + 0.7107068705f; q = q * t + (-0.142248368f); q = q * t + 0.127414796f; q = q * t;
;     const f32x2 s = (v * v) * (-0.72134752044f);
;     f32x2 e; e.x = __builtin_amdgcn_exp2f(s.x); e.y = __builtin_amdgcn_exp2f(s.y);
;     const f32x2 m = v * (q * e), r = v - m;
;     f32x2 o; o.x = v.x < 0.f ? m.x : r.x; o.y = v.y < 0.f ? m.y : r.y; return o;
;     __device__ __forceinline__ void operator()(const f32x4 (&acc)[2][2][4][2], const Unit& u, int wr, int wc, int fr, int fq) const {
;     ...
;                 for (int bj = 0; bj < 2; ++bj) { f32x4 v0 = acc[ai][bj][m][0] * rs, v1 = acc[ai][bj][m][1] * rs;
;                     const f32x2 a = gelu_pk((f32x2){v0[0], v0[1]}), b = gelu_pk((f32x2){v0[2], v0[3]}), c = gelu_pk((f32x2){v1[0], v1[1]}), d = gelu_pk((f32x2){v1[2], v1[3]});
;                     s1 += ((a.x + a.y) + (b.x + b.y)) + ((c.x + c.y) + (d.x + d.y));
;                     s2 += ((a.x * a.x + a.y * a.y) + (b.x * b.x + b.y * b.y)) + ((c.x * c.x + c.y * c.y) + (d.x * d.x + d.y * d.y));
;                     u32x4 w; w.x = cvt_pk_bf16(a.x, a.y); w.y = cvt_pk_bf16(b.x, b.y); w.z = cvt_pk_bf16(c.x, c.y); w.w = cvt_pk_bf16(d.x, d.y);
;                     *(u32x4*)(rowp + bj * HALF) = w; }
	v_pk_fma_f32 v[202:203], v[192:193], s[66:67], v[150:151] op_sel_hi:[1,0,0]
	s_nop 0
	v_pk_fma_f32 v[202:203], v[192:193], v[202:203], s[70:71] op_sel_hi:[1,1,0]
	s_nop 0
	v_pk_fma_f32 v[202:203], v[192:193], v[202:203], s[72:73] op_sel_hi:[1,1,0]
	s_nop 0
	v_pk_fma_f32 v[202:203], v[192:193], v[202:203], s[74:75] op_sel_hi:[1,1,0]
	s_nop 0
	v_pk_mul_f32 v[192:193], v[192:193], v[202:203]
	v_cvt_pk_bf16_f32 v202, v178, v179
	v_cvt_pk_bf16_f32 v203, v189, v190
	v_cvt_pk_bf16_f32 v204, v154, v155
	s_nop 0
	v_pk_mul_f32 v[156:157], v[156:157], v[192:193]
	s_nop 0
	v_max_f32_e32 v192, 0, v152
	v_max_f32_e32 v193, 0, v153
	v_fma_f32 v152, -|v152|, v156, v192
	v_fma_f32 v153, -|v153|, v157, v193
	s_nop 0
	s_nop 0
	s_nop 0
	s_nop 1
	s_nop 0
	v_pk_mul_f32 v[156:157], v[138:139], v[0:1] op_sel_hi:[1,0]
	v_and_b32_e32 v139, 0x7fffffff, v143
	v_and_b32_e32 v138, 0x7fffffff, v142
	v_pk_fma_f32 v[138:139], v[138:139], s[64:65], 1.0 op_sel_hi:[1,0,0]
	v_cvt_pk_bf16_f32 v205, v152, v153
	global_store_dwordx4 v[176:177], v[202:205], off
	v_rcp_f32_e32 v138, v138
	v_rcp_f32_e32 v139, v139
	v_pk_mul_f32 v[202:203], v[142:143], v[142:143]
	s_nop 0
	v_pk_mul_f32 v[202:203], v[202:203], s[76:77] op_sel_hi:[1,0]
	v_pk_fma_f32 v[192:193], v[138:139], s[66:67], v[150:151] op_sel_hi:[1,0,0]
	v_exp_f32_e32 v202, v202
	v_pk_fma_f32 v[192:193], v[138:139], v[192:193], s[70:71] op_sel_hi:[1,1,0]
	v_exp_f32_e32 v203, v203
	v_pk_fma_f32 v[192:193], v[138:139], v[192:193], s[72:73] op_sel_hi:[1,1,0]
	s_nop 0
	v_pk_fma_f32 v[192:193], v[138:139], v[192:193], s[74:75] op_sel_hi:[1,1,0]
	s_nop 0
	v_pk_mul_f32 v[138:139], v[138:139], v[192:193]
	v_pk_mul_f32 v[192:193], v[144:145], v[144:145]
	v_pk_mul_f32 v[138:139], v[202:203], v[138:139]
	v_pk_mul_f32 v[192:193], v[192:193], s[76:77] op_sel_hi:[1,0]
	v_max_f32_e32 v202, 0, v142
	v_max_f32_e32 v203, 0, v143
	v_fma_f32 v0, -|v142|, v138, v202
	v_fma_f32 v138, -|v143|, v139, v203
	v_and_b32_e32 v142, 0x7fffffff, v144
	s_nop 0
	s_nop 0
	v_and_b32_e32 v143, 0x7fffffff, v145
	v_pk_fma_f32 v[142:143], v[142:143], s[64:65], 1.0 op_sel_hi:[1,0,0]
	s_nop 0
	v_rcp_f32_e32 v142, v142
	v_rcp_f32_e32 v143, v143
	v_exp_f32_e32 v192, v192
	v_exp_f32_e32 v193, v193
	s_nop 0
	v_pk_fma_f32 v[202:203], v[142:143], s[66:67], v[150:151] op_sel_hi:[1,0,0]
	s_nop 0
	v_pk_fma_f32 v[202:203], v[142:143], v[202:203], s[70:71] op_sel_hi:[1,1,0]
	s_nop 0
	v_pk_fma_f32 v[202:203], v[142:143], v[202:203], s[72:73] op_sel_hi:[1,1,0]
	s_nop 0
	v_pk_fma_f32 v[202:203], v[142:143], v[202:203], s[74:75] op_sel_hi:[1,1,0]
	s_nop 0
	v_pk_mul_f32 v[142:143], v[142:143], v[202:203]
	v_pk_mul_f32 v[202:203], v[156:157], v[156:157]
	v_pk_mul_f32 v[142:143], v[192:193], v[142:143]
	v_pk_mul_f32 v[202:203], v[202:203], s[76:77] op_sel_hi:[1,0]
	v_max_f32_e32 v192, 0, v144
	v_max_f32_e32 v193, 0, v145
	v_fma_f32 v139, -|v144|, v142, v192
	v_fma_f32 v142, -|v145|, v143, v193
	v_and_b32_e32 v144, 0x7fffffff, v156
	s_nop 0
	s_nop 0
	v_and_b32_e32 v145, 0x7fffffff, v157
	v_pk_fma_f32 v[144:145], v[144:145], s[64:65], 1.0 op_sel_hi:[1,0,0]
	s_nop 0
	v_rcp_f32_e32 v144, v144
	v_rcp_f32_e32 v145, v145
	v_exp_f32_e32 v202, v202
	v_exp_f32_e32 v203, v203
	s_nop 0
	v_pk_fma_f32 v[192:193], v[144:145], s[66:67], v[150:151] op_sel_hi:[1,0,0]
	s_nop 0
	v_pk_fma_f32 v[192:193], v[144:145], v[192:193], s[70:71] op_sel_hi:[1,1,0]
	s_nop 0
	v_pk_fma_f32 v[192:193], v[144:145], v[192:193], s[72:73] op_sel_hi:[1,1,0]
	s_nop 0
	v_pk_fma_f32 v[192:193], v[144:145], v[192:193], s[74:75] op_sel_hi:[1,1,0]
	s_nop 0
	v_pk_mul_f32 v[144:145], v[144:145], v[192:193]
	v_pk_mul_f32 v[192:193], v[140:141], v[140:141]
	v_pk_mul_f32 v[144:145], v[202:203], v[144:145]
	s_nop 0
	v_max_f32_e32 v202, 0, v156
	v_max_f32_e32 v203, 0, v157
	v_fma_f32 v143, -|v156|, v144, v202
	v_fma_f32 v144, -|v157|, v145, v203
	v_and_b32_e32 v156, 0x7fffffff, v140
	s_nop 0
	s_nop 0
	v_and_b32_e32 v157, 0x7fffffff, v141
	v_pk_fma_f32 v[156:157], v[156:157], s[64:65], 1.0 op_sel_hi:[1,0,0]
	s_nop 0
	v_rcp_f32_e32 v156, v156
	v_rcp_f32_e32 v157, v157
	s_nop 0
	v_cvt_pk_bf16_f32 v202, v0, v138
	v_cvt_pk_bf16_f32 v203, v139, v142
	v_pk_fma_f32 v[150:151], v[156:157], s[66:67], v[150:151] op_sel_hi:[1,0,0]
	v_cvt_pk_bf16_f32 v204, v143, v144
	s_nop 0
	v_pk_fma_f32 v[150:151], v[156:157], v[150:151], s[70:71] op_sel_hi:[1,1,0]
	s_nop 0
	v_pk_fma_f32 v[150:151], v[156:157], v[150:151], s[72:73] op_sel_hi:[1,1,0]
	s_nop 0
	v_pk_fma_f32 v[150:151], v[156:157], v[150:151], s[74:75] op_sel_hi:[1,1,0]
	s_nop 0
	v_pk_mul_f32 v[150:151], v[156:157], v[150:151]
	v_pk_mul_f32 v[156:157], v[192:193], s[76:77] op_sel_hi:[1,0]
	s_nop 0
	v_exp_f32_e32 v156, v156
	v_exp_f32_e32 v157, v157
	s_nop 0
	v_pk_mul_f32 v[150:151], v[156:157], v[150:151]
	s_nop 0
	v_max_f32_e32 v156, 0, v140
	v_max_f32_e32 v157, 0, v141
	v_fma_f32 v140, -|v140|, v150, v156
	v_fma_f32 v141, -|v141|, v151, v157
	s_nop 0
	s_nop 0
	s_nop 0
	s_nop 1
	s_nop 0
	v_cvt_pk_bf16_f32 v205, v140, v141
	global_store_dwordx4 v[176:177], v[202:205], off offset:256
	s_cbranch_scc1 .LBB0_356
; __device__ __forceinline__ unsigned cvt_pk_bf16(float lo, float hi) { unsigned r; asm volatile("v_cvt_pk_bf16_f32 %0, %1, %2" : "=v"(r) : "v"(lo), "v"(hi)); return r; }
;     __device__ __forceinline__ void operator()(const f32x4 (&acc)[2][2][4][2], const Unit& u, int wr, int wc, int fr, int fq) const {
;     ...
;                     s1 += ((a.x + a.y) + (b.x + b.y)) + ((c.x + c.y) + (d.x + d.y));
;                     s2 += ((a.x * a.x + a.y * a.y) + (b.x * b.x + b.y * b.y)) + ((c.x * c.x + c.y * c.y) + (d.x * d.x + d.y * d.y));
;                     u32x4 w; w.x = cvt_pk_bf16(a.x, a.y); w.y = cvt_pk_bf16(b.x, b.y); w.z = cvt_pk_bf16(c.x, c.y); w.w = cvt_pk_bf16(d.x, d.y);
;                     *(u32x4*)(rowp + bj * HALF) = w; }
;                 if (isv) { s1 += __shfl_xor(s1, 16); s1 += __shfl_xor(s1, 32); s2 += __shfl_xor(s2, 16); s2 += __shfl_xor(s2, 32);
;                     if (fq == 0) { const int rl = ai * HALF + wr * 64 + m * 16 + fr; part[rl * 4 + wc] = s1; part[1024 + rl * 4 + wc] = s2; } } }
	v_mul_f32_e32 v145, v179, v179
	v_mul_f32_e32 v150, v190, v190
	v_fmac_f32_e32 v145, v178, v178
	v_fmac_f32_e32 v150, v189, v189
	v_add_f32_e32 v145, v145, v150
	v_mul_f32_e32 v150, v155, v155
	v_mul_f32_e32 v151, v153, v153
	v_fmac_f32_e32 v150, v154, v154
	v_fmac_f32_e32 v151, v152, v152
	v_add_f32_e32 v150, v150, v151
	v_add_f32_e32 v145, v145, v150
	v_mul_f32_e32 v150, v138, v138
	v_fmac_f32_e32 v150, v0, v0
	v_mul_f32_e32 v151, v142, v142
	v_add_f32_e32 v0, v0, v138
	v_add_f32_e32 v138, v139, v142
	v_fmac_f32_e32 v151, v139, v139
	v_add_f32_e32 v0, v0, v138
	v_add_f32_e32 v138, v143, v144
	v_add_f32_e32 v139, v140, v141
	v_add_f32_e32 v157, v178, v179
	v_add_f32_e32 v176, v189, v190
	v_add_f32_e32 v154, v154, v155
	v_add_f32_e32 v152, v152, v153
	v_add_f32_e32 v138, v138, v139
	v_and_b32_e32 v139, 64, v226
	v_add_f32_e32 v157, v157, v176
	v_add_f32_e32 v152, v154, v152
	v_add_f32_e32 v0, v0, v138
	v_xor_b32_e32 v138, 16, v226
	v_add_u32_e32 v139, 64, v139
	v_add_f32_e32 v152, v157, v152
	v_cmp_lt_i32_e32 vcc, v138, v139
	v_add_f32_e32 v150, v150, v151
	v_mul_f32_e32 v151, v144, v144
	v_mul_f32_e32 v156, v141, v141
	v_add_f32_e32 v152, 0, v152
	v_cndmask_b32_e32 v138, v226, v138, vcc
	v_fmac_f32_e32 v151, v143, v143
	v_add_f32_e32 v0, v0, v152
	v_lshlrev_b32_e32 v138, 2, v138
	v_fmac_f32_e32 v156, v140, v140
	v_mov_b32_e32 v141, v0
	s_nop 1
	v_permlane16_swap_b32_e32 v141, v0
	v_add_f32_e32 v140, v151, v156
	v_add_f32_e32 v140, v150, v140
	v_add_f32_e32 v140, v145, v140
	v_mov_b32_e32 v142, v140
	s_nop 1
	v_permlane16_swap_b32_e32 v142, v140
	s_waitcnt lgkmcnt(0)
	v_add_f32_e32 v0, v0, v141
	v_xor_b32_e32 v141, 32, v226
	v_cmp_lt_i32_e32 vcc, v141, v139
	v_add_f32_e32 v139, v140, v142
	s_nop 0
	v_cndmask_b32_e32 v138, v226, v141, vcc
	v_lshlrev_b32_e32 v141, 2, v138
	v_mov_b32_e32 v138, v0
	s_nop 1
	v_permlane32_swap_b32_e32 v138, v0
	v_mov_b32_e32 v140, v139
	s_nop 1
	v_permlane32_swap_b32_e32 v140, v139
	s_and_saveexec_b64 s[4:5], s[6:7]
	s_cbranch_execz .LBB0_355
	s_waitcnt lgkmcnt(0)
	v_add_f32_e32 v139, v139, v140
	v_add_f32_e32 v0, v0, v138
	ds_write2st64_b32 v186, v0, v139 offset1:16

; __device__ __forceinline__ unsigned cvt_pk_bf16(float lo, float hi) { unsigned r; asm volatile("v_cvt_pk_bf16_f32 %0, %1, %2" : "=v"(r) : "v"(lo), "v"(hi)); return r; }
; __device__ __forceinline__ f32x2 gelu_pk(f32x2 v) {
;     const f32x2 av = __builtin_elementwise_abs(v), d = av * 0.2316418882f + 1.0f;
;     f32x2 t; t.x = __builtin_amdgcn_rcpf(d.x); t.y = __builtin_amdgcn_rcpf(d.y);
;     f32x2 q = t * 0.5307027145f + (-0.7265760135f); q = q * t + 0.7107068705f; q = q * t + (-0.142248368f); q = q * t + 0.127414796f; q = q * t;
;     const f32x2 s = (v * v) * (-0.72134752044f);
;     f32x2 e; e.x = __builtin_amdgcn_exp2f(s.x); e.y = __builtin_amdgcn_exp2f(s.y);
;     const f32x2 m = v * (q * e), r = v - m;
;     f32x2 o; o.x = v.x < 0.f ? m.x : r.x; o.y = v.y < 0.f ? m.y : r.y; return o;
;     __device__ __forceinline__ void operator()(const f32x4 (&acc)[2][2][4][2], const Unit& u, int wr, int wc, int fr, int fq) const {
;     ...
;             for (int m = 0; m < 4; ++m) { const int row = row0 + ai * HALF + m * 16; const float rs = rsv[ai][m]; bf16_t* rowp = O + (size_t)row * ldc + col0; float s1 = 0.f, s2 = 0.f;
; #pragma unroll
;                 for (int bj = 0; bj < 2; ++bj) { f32x4 v0 = acc[ai][bj][m][0] * rs, v1 = acc[ai][bj][m][1] * rs;
;                     const f32x2 a = gelu_pk((f32x2){v0[0], v0[1]}), b = gelu_pk((f32x2){v0[2], v0[3]}), c = gelu_pk((f32x2){v1[0], v1[1]}), d = gelu_pk((f32x2){v1[2], v1[3]});
;                     s1 += ((a.x + a.y) + (b.x + b.y)) + ((c.x + c.y) + (d.x + d.y));
;                     s2 += ((a.x * a.x + a.y * a.y) + (b.x * b.x + b.y * b.y)) + ((c.x * c.x + c.y * c.y) + (d.x * d.x + d.y * d.y));
;                     u32x4 w; w.x = cvt_pk_bf16(a.x, a.y); w.y = cvt_pk_bf16(b.x, b.y); w.z = cvt_pk_bf16(c.x, c.y); w.w = cvt_pk_bf16(d.x, d.y);
;                     *(u32x4*)(rowp + bj * HALF) = w; }
.LBB0_356:
	v_add_f32_e32 v0, v146, v147
	s_waitcnt lgkmcnt(0)
	v_add_f32_e32 v138, v148, v149
	v_add_f32_e32 v0, v0, v138
	v_fmamk_f32 v0, v0, 0x3a800000, v224
	v_rsq_f32_e32 v0, v0
	s_mov_b32 s4, 0xbf3a00e3
	v_lshlrev_b64 v[138:139], 12, v[174:175]
	v_lshl_add_u64 v[138:139], s[20:21], 0, v[138:139]
	v_pk_mul_f32 v[134:135], v[134:135], v[0:1] op_sel_hi:[1,0]
	v_pk_mul_f32 v[140:141], v[130:131], v[0:1] op_sel_hi:[1,0]
	v_and_b32_e32 v131, 0x7fffffff, v135
	v_and_b32_e32 v130, 0x7fffffff, v134
	v_pk_fma_f32 v[130:131], v[130:131], s[64:65], 1.0 op_sel_hi:[1,0,0]
	v_pk_mul_f32 v[146:147], v[134:135], v[134:135]
	v_rcp_f32_e32 v142, v130
	v_rcp_f32_e32 v143, v131
	v_mov_b64_e32 v[130:131], s[4:5]
	v_pk_mul_f32 v[146:147], v[146:147], s[76:77] op_sel_hi:[1,0]
	s_nop 0
	v_pk_fma_f32 v[144:145], v[142:143], s[66:67], v[130:131] op_sel_hi:[1,0,0]
	v_exp_f32_e32 v146, v146
	v_pk_fma_f32 v[144:145], v[142:143], v[144:145], s[70:71] op_sel_hi:[1,1,0]
	v_exp_f32_e32 v147, v147
	v_pk_fma_f32 v[144:145], v[142:143], v[144:145], s[72:73] op_sel_hi:[1,1,0]
	v_pk_mul_f32 v[136:137], v[136:137], v[0:1] op_sel_hi:[1,0]
	v_pk_fma_f32 v[144:145], v[142:143], v[144:145], s[74:75] op_sel_hi:[1,1,0]
	v_pk_mul_f32 v[132:133], v[132:133], v[0:1] op_sel_hi:[1,0]
	v_pk_mul_f32 v[142:143], v[142:143], v[144:145]
	v_pk_mul_f32 v[144:145], v[136:137], v[136:137]
	v_pk_mul_f32 v[142:143], v[146:147], v[142:143]
	v_pk_mul_f32 v[144:145], v[144:145], s[76:77] op_sel_hi:[1,0]
	v_max_f32_e32 v146, 0, v134
	v_max_f32_e32 v147, 0, v135
	v_fma_f32 v134, -|v134|, v142, v146
	v_fma_f32 v135, -|v135|, v143, v147
	v_exp_f32_e32 v144, v144
	s_nop 0
	s_nop 0
	v_and_b32_e32 v142, 0x7fffffff, v136
	v_exp_f32_e32 v145, v145
	s_nop 0
	v_and_b32_e32 v143, 0x7fffffff, v137
	v_pk_fma_f32 v[142:143], v[142:143], s[64:65], 1.0 op_sel_hi:[1,0,0]
	s_nop 0
	v_rcp_f32_e32 v142, v142
	v_rcp_f32_e32 v143, v143
	v_lshl_add_u64 v[138:139], v[160:161], 1, v[138:139]
	v_pk_mul_f32 v[122:123], v[122:123], v[0:1] op_sel_hi:[1,0]
	v_pk_mul_f32 v[124:125], v[124:125], v[0:1] op_sel_hi:[1,0]
	v_pk_fma_f32 v[146:147], v[142:143], s[66:67], v[130:131] op_sel_hi:[1,0,0]
	v_pk_mul_f32 v[120:121], v[120:121], v[0:1] op_sel_hi:[1,0]
	v_pk_fma_f32 v[146:147], v[142:143], v[146:147], s[70:71] op_sel_hi:[1,1,0]
	s_nop 0
	v_pk_fma_f32 v[146:147], v[142:143], v[146:147], s[72:73] op_sel_hi:[1,1,0]
	s_nop 0
	v_pk_fma_f32 v[146:147], v[142:143], v[146:147], s[74:75] op_sel_hi:[1,1,0]
	s_nop 0
	v_pk_mul_f32 v[142:143], v[142:143], v[146:147]
	v_pk_mul_f32 v[146:147], v[140:141], v[140:141]
	v_pk_mul_f32 v[142:143], v[144:145], v[142:143]
	v_pk_mul_f32 v[146:147], v[146:147], s[76:77] op_sel_hi:[1,0]
	v_max_f32_e32 v144, 0, v136
	v_max_f32_e32 v145, 0, v137
	v_fma_f32 v136, -|v136|, v142, v144
	v_fma_f32 v137, -|v137|, v143, v145
	v_exp_f32_e32 v146, v146
	s_nop 0
	s_nop 0
	v_and_b32_e32 v142, 0x7fffffff, v140
	v_exp_f32_e32 v147, v147
	s_nop 0
	v_and_b32_e32 v143, 0x7fffffff, v141
	v_pk_fma_f32 v[142:143], v[142:143], s[64:65], 1.0 op_sel_hi:[1,0,0]
	s_nop 0
	v_rcp_f32_e32 v142, v142
	v_rcp_f32_e32 v143, v143
	s_nop 0
	v_pk_fma_f32 v[144:145], v[142:143], s[66:67], v[130:131] op_sel_hi:[1,0,0]
	s_nop 0
	v_pk_fma_f32 v[144:145], v[142:143], v[144:145], s[70:71] op_sel_hi:[1,1,0]
	s_nop 0
	v_pk_fma_f32 v[144:145], v[142:143], v[144:145], s[72:73] op_sel_hi:[1,1,0]
	s_nop 0
	v_pk_fma_f32 v[144:145], v[142:143], v[144:145], s[74:75] op_sel_hi:[1,1,0]
	s_nop 0
	v_pk_mul_f32 v[142:143], v[142:143], v[144:145]
	v_pk_mul_f32 v[144:145], v[132:133], v[132:133]
	v_pk_mul_f32 v[142:143], v[146:147], v[142:143]
	v_pk_mul_f32 v[144:145], v[144:145], s[76:77] op_sel_hi:[1,0]
	v_max_f32_e32 v146, 0, v140
	v_max_f32_e32 v147, 0, v141
	v_fma_f32 v140, -|v140|, v142, v146
	v_fma_f32 v141, -|v141|, v143, v147
	v_exp_f32_e32 v144, v144
	s_nop 0
	s_nop 0
	v_and_b32_e32 v142, 0x7fffffff, v132
	v_exp_f32_e32 v145, v145
	s_nop 0
	v_and_b32_e32 v143, 0x7fffffff, v133
	v_pk_fma_f32 v[142:143], v[142:143], s[64:65], 1.0 op_sel_hi:[1,0,0]
	s_nop 0
	v_rcp_f32_e32 v142, v142
	v_rcp_f32_e32 v143, v143
	s_nop 0
	v_pk_fma_f32 v[146:147], v[142:143], s[66:67], v[130:131] op_sel_hi:[1,0,0]
	s_nop 0
	v_pk_fma_f32 v[146:147], v[142:143], v[146:147], s[70:71] op_sel_hi:[1,1,0]
	s_nop 0
	v_pk_fma_f32 v[146:147], v[142:143], v[146:147], s[72:73] op_sel_hi:[1,1,0]
	s_nop 0
	v_pk_fma_f32 v[146:147], v[142:143], v[146:147], s[74:75] op_sel_hi:[1,1,0]
	s_nop 0
	v_pk_mul_f32 v[142:143], v[142:143], v[146:147]
	v_pk_mul_f32 v[146:147], v[122:123], v[122:123]
	v_pk_mul_f32 v[142:143], v[144:145], v[142:143]
	v_pk_mul_f32 v[146:147], v[146:147], s[76:77] op_sel_hi:[1,0]
	v_max_f32_e32 v144, 0, v132
	v_max_f32_e32 v145, 0, v133
	v_fma_f32 v132, -|v132|, v142, v144
	v_fma_f32 v133, -|v133|, v143, v145
	v_exp_f32_e32 v146, v146
	s_nop 0
	s_nop 0
	v_cvt_pk_bf16_f32 v142, v134, v135
	v_exp_f32_e32 v147, v147
	s_nop 0
	s_nop 0
	v_cvt_pk_bf16_f32 v143, v136, v137
	v_cvt_pk_bf16_f32 v144, v140, v141
	v_cvt_pk_bf16_f32 v145, v132, v133
	global_store_dwordx4 v[138:139], v[142:145], off
	s_nop 0
	s_nop 0
	v_pk_mul_f32 v[142:143], v[118:119], v[0:1] op_sel_hi:[1,0]
	v_and_b32_e32 v119, 0x7fffffff, v123
	v_and_b32_e32 v118, 0x7fffffff, v122
	v_pk_fma_f32 v[118:119], v[118:119], s[64:65], 1.0 op_sel_hi:[1,0,0]
	s_nop 0
	v_rcp_f32_e32 v118, v118
	v_rcp_f32_e32 v119, v119
	s_nop 0
	v_pk_fma_f32 v[144:145], v[118:119], s[66:67], v[130:131] op_sel_hi:[1,0,0]
	s_nop 0
	v_pk_fma_f32 v[144:145], v[118:119], v[144:145], s[70:71] op_sel_hi:[1,1,0]
	s_nop 0
	v_pk_fma_f32 v[144:145], v[118:119], v[144:145], s[72:73] op_sel_hi:[1,1,0]
	s_nop 0
	v_pk_fma_f32 v[144:145], v[118:119], v[144:145], s[74:75] op_sel_hi:[1,1,0]
; __device__ __forceinline__ unsigned cvt_pk_bf16(float lo, float hi) { unsigned r; asm volatile("v_cvt_pk_bf16_f32 %0, %1, %2" : "=v"(r) : "v"(lo), "v"(hi)); return r; }
; __device__ __forceinline__ f32x2 gelu_pk(f32x2 v) {
;     const f32x2 av = __builtin_elementwise_abs(v), d = av * 0.2316418882f + 1.0f;
;     f32x2 t; t.x = __builtin_amdgcn_rcpf(d.x); t.y = __builtin_amdgcn_rcpf(d.y);
;     f32x2 q = t * 0.5307027145f + (-0.7265760135f); q = q * t + 0.7107068705f; q = q * t + (-0.142248368f); q = q * t + 0.127414796f; q = q * t;
;     const f32x2 s = (v * v) * (-0.72134752044f);
;     f32x2 e; e.x = __builtin_amdgcn_exp2f(s.x); e.y = __builtin_amdgcn_exp2f(s.y);
;     const f32x2 m = v * (q * e), r = v - m;
;     f32x2 o; o.x = v.x < 0.f ? m.x : r.x; o.y = v.y < 0.f ? m.y : r.y; return o;
;     __device__ __forceinline__ void operator()(const f32x4 (&acc)[2][2][4][2], const Unit& u, int wr, int wc, int fr, int fq) const {
;     ...
;                 for (int bj = 0; bj < 2; ++bj) { f32x4 v0 = acc[ai][bj][m][0] * rs, v1 = acc[ai][bj][m][1] * rs;
;                     const f32x2 a = gelu_pk((f32x2){v0[0], v0[1]}), b = gelu_pk((f32x2){v0[2], v0[3]}), c = gelu_pk((f32x2){v1[0], v1[1]}), d = gelu_pk((f32x2){v1[2], v1[3]});
;                     s1 += ((a.x + a.y) + (b.x + b.y)) + ((c.x + c.y) + (d.x + d.y));
;                     s2 += ((a.x * a.x + a.y * a.y) + (b.x * b.x + b.y * b.y)) + ((c.x * c.x + c.y * c.y) + (d.x * d.x + d.y * d.y));
;                     u32x4 w; w.x = cvt_pk_bf16(a.x, a.y); w.y = cvt_pk_bf16(b.x, b.y); w.z = cvt_pk_bf16(c.x, c.y); w.w = cvt_pk_bf16(d.x, d.y);
;                     *(u32x4*)(rowp + bj * HALF) = w; }
;                 if (isv) { s1 += __shfl_xor(s1, 16); s1 += __shfl_xor(s1, 32); s2 += __shfl_xor(s2, 16); s2 += __shfl_xor(s2, 32);
;                     if (fq == 0) { const int rl = ai * HALF + wr * 64 + m * 16 + fr; part[rl * 4 + wc] = s1; part[1024 + rl * 4 + wc] = s2; } } }
	s_nop 0
	v_pk_mul_f32 v[118:119], v[118:119], v[144:145]
	v_pk_mul_f32 v[144:145], v[124:125], v[124:125]
	v_pk_mul_f32 v[118:119], v[146:147], v[118:119]
	v_pk_mul_f32 v[144:145], v[144:145], s[76:77] op_sel_hi:[1,0]
	v_max_f32_e32 v146, 0, v122
	v_max_f32_e32 v147, 0, v123
	v_fma_f32 v0, -|v122|, v118, v146
	v_fma_f32 v118, -|v123|, v119, v147
	v_and_b32_e32 v122, 0x7fffffff, v124
	s_nop 0
	s_nop 0
	v_and_b32_e32 v123, 0x7fffffff, v125
	v_pk_fma_f32 v[122:123], v[122:123], s[64:65], 1.0 op_sel_hi:[1,0,0]
	s_nop 0
	v_rcp_f32_e32 v122, v122
	v_rcp_f32_e32 v123, v123
	v_exp_f32_e32 v144, v144
	v_exp_f32_e32 v145, v145
	s_nop 0
	v_pk_fma_f32 v[146:147], v[122:123], s[66:67], v[130:131] op_sel_hi:[1,0,0]
	s_nop 0
	v_pk_fma_f32 v[146:147], v[122:123], v[146:147], s[70:71] op_sel_hi:[1,1,0]
	s_nop 0
	v_pk_fma_f32 v[146:147], v[122:123], v[146:147], s[72:73] op_sel_hi:[1,1,0]
	s_nop 0
	v_pk_fma_f32 v[146:147], v[122:123], v[146:147], s[74:75] op_sel_hi:[1,1,0]
	s_nop 0
	v_pk_mul_f32 v[122:123], v[122:123], v[146:147]
	v_pk_mul_f32 v[146:147], v[142:143], v[142:143]
	v_pk_mul_f32 v[122:123], v[144:145], v[122:123]
	v_pk_mul_f32 v[146:147], v[146:147], s[76:77] op_sel_hi:[1,0]
	v_max_f32_e32 v144, 0, v124
	v_max_f32_e32 v145, 0, v125
	v_fma_f32 v119, -|v124|, v122, v144
	v_fma_f32 v122, -|v125|, v123, v145
	v_and_b32_e32 v124, 0x7fffffff, v142
	s_nop 0
	s_nop 0
	v_and_b32_e32 v125, 0x7fffffff, v143
	v_pk_fma_f32 v[124:125], v[124:125], s[64:65], 1.0 op_sel_hi:[1,0,0]
	s_nop 0
	v_rcp_f32_e32 v124, v124
	v_rcp_f32_e32 v125, v125
	v_exp_f32_e32 v146, v146
	v_exp_f32_e32 v147, v147
	s_nop 0
	v_pk_fma_f32 v[144:145], v[124:125], s[66:67], v[130:131] op_sel_hi:[1,0,0]
	s_nop 0
	v_pk_fma_f32 v[144:145], v[124:125], v[144:145], s[70:71] op_sel_hi:[1,1,0]
	s_nop 0
	v_pk_fma_f32 v[144:145], v[124:125], v[144:145], s[72:73] op_sel_hi:[1,1,0]
	s_nop 0
	v_pk_fma_f32 v[144:145], v[124:125], v[144:145], s[74:75] op_sel_hi:[1,1,0]
	s_nop 0
	v_pk_mul_f32 v[124:125], v[124:125], v[144:145]
	v_pk_mul_f32 v[144:145], v[120:121], v[120:121]
	v_pk_mul_f32 v[124:125], v[146:147], v[124:125]
	s_nop 0
	v_max_f32_e32 v146, 0, v142
	v_max_f32_e32 v147, 0, v143
	v_fma_f32 v123, -|v142|, v124, v146
	v_fma_f32 v124, -|v143|, v125, v147
	v_and_b32_e32 v142, 0x7fffffff, v120
	s_nop 0
	s_nop 0
	v_and_b32_e32 v143, 0x7fffffff, v121
	v_pk_fma_f32 v[142:143], v[142:143], s[64:65], 1.0 op_sel_hi:[1,0,0]
	s_nop 0
	v_rcp_f32_e32 v142, v142
	v_rcp_f32_e32 v143, v143
	s_nop 0
	v_cndmask_b32_e64 v125, 0, 1, s[36:37]
	v_cmp_ne_u32_e64 s[10:11], 1, v125
	v_pk_fma_f32 v[130:131], v[142:143], s[66:67], v[130:131] op_sel_hi:[1,0,0]
	s_nop 0
	v_pk_fma_f32 v[130:131], v[142:143], v[130:131], s[70:71] op_sel_hi:[1,1,0]
	s_nop 0
	v_pk_fma_f32 v[130:131], v[142:143], v[130:131], s[72:73] op_sel_hi:[1,1,0]
	s_nop 0
	v_pk_fma_f32 v[130:131], v[142:143], v[130:131], s[74:75] op_sel_hi:[1,1,0]
	s_nop 0
	v_pk_mul_f32 v[130:131], v[142:143], v[130:131]
	v_pk_mul_f32 v[142:143], v[144:145], s[76:77] op_sel_hi:[1,0]
	s_nop 0
	v_exp_f32_e32 v142, v142
	v_exp_f32_e32 v143, v143
	s_nop 0
	v_pk_mul_f32 v[130:131], v[142:143], v[130:131]
	s_nop 0
	v_max_f32_e32 v142, 0, v120
	v_max_f32_e32 v143, 0, v121
	v_fma_f32 v120, -|v120|, v130, v142
	v_fma_f32 v121, -|v121|, v131, v143
	s_nop 0
	s_nop 0
	s_nop 0
	v_cvt_pk_bf16_f32 v142, v0, v118
	s_nop 1
	s_nop 0
	s_andn2_b64 vcc, exec, s[36:37]
	v_cvt_pk_bf16_f32 v143, v119, v122
	v_cvt_pk_bf16_f32 v144, v123, v124
	v_cvt_pk_bf16_f32 v145, v120, v121
	global_store_dwordx4 v[138:139], v[142:145], off offset:256
	s_cbranch_vccnz .LBB0_360
	v_mul_f32_e32 v125, v135, v135
	v_mul_f32_e32 v130, v137, v137
	v_fmac_f32_e32 v125, v134, v134
	v_fmac_f32_e32 v130, v136, v136
	v_add_f32_e32 v125, v125, v130
	v_mul_f32_e32 v130, v141, v141
	v_mul_f32_e32 v131, v133, v133
	v_fmac_f32_e32 v130, v140, v140
	v_fmac_f32_e32 v131, v132, v132
	v_add_f32_e32 v130, v130, v131
	v_add_f32_e32 v125, v125, v130
	v_mul_f32_e32 v130, v118, v118
	v_fmac_f32_e32 v130, v0, v0
	v_mul_f32_e32 v131, v122, v122
	v_add_f32_e32 v0, v0, v118
	v_add_f32_e32 v118, v119, v122
	v_fmac_f32_e32 v131, v119, v119
	v_add_f32_e32 v134, v134, v135
	v_add_f32_e32 v135, v136, v137
	v_add_f32_e32 v0, v0, v118
	v_add_f32_e32 v118, v123, v124
	v_add_f32_e32 v119, v120, v121
	v_add_f32_e32 v134, v134, v135
	v_add_f32_e32 v135, v140, v141
	v_add_f32_e32 v132, v132, v133
	v_add_f32_e32 v118, v118, v119
	v_and_b32_e32 v119, 64, v226
	v_add_f32_e32 v132, v135, v132
	v_add_f32_e32 v0, v0, v118
	v_xor_b32_e32 v118, 16, v226
	v_add_u32_e32 v119, 64, v119
	v_add_f32_e32 v132, v134, v132
	v_cmp_lt_i32_e32 vcc, v118, v119
	v_add_f32_e32 v130, v130, v131
	v_mul_f32_e32 v131, v124, v124
	v_mul_f32_e32 v138, v121, v121
	v_add_f32_e32 v132, 0, v132
	v_cndmask_b32_e32 v118, v226, v118, vcc
	v_fmac_f32_e32 v131, v123, v123
	v_add_f32_e32 v0, v0, v132
	v_lshlrev_b32_e32 v118, 2, v118
	v_fmac_f32_e32 v138, v120, v120
	v_mov_b32_e32 v121, v0
	s_nop 1
	v_permlane16_swap_b32_e32 v121, v0
	v_add_f32_e32 v120, v131, v138
	v_add_f32_e32 v120, v130, v120
	v_add_f32_e32 v120, v125, v120
	v_mov_b32_e32 v122, v120
	s_nop 1
	v_permlane16_swap_b32_e32 v122, v120
	s_waitcnt lgkmcnt(0)
	v_add_f32_e32 v0, v0, v121
	v_xor_b32_e32 v121, 32, v226
	v_cmp_lt_i32_e32 vcc, v121, v119
	v_add_f32_e32 v119, v120, v122
	s_nop 0
	v_cndmask_b32_e32 v118, v226, v121, vcc
	v_lshlrev_b32_e32 v121, 2, v118
	v_mov_b32_e32 v118, v0
	s_nop 1
	v_permlane32_swap_b32_e32 v118, v0
	v_mov_b32_e32 v120, v119
	s_nop 1
	v_permlane32_swap_b32_e32 v120, v119
	s_and_saveexec_b64 s[4:5], s[6:7]
	s_cbranch_execz .LBB0_359
	s_waitcnt lgkmcnt(0)
	v_add_f32_e32 v119, v119, v120
	v_add_f32_e32 v0, v0, v118
	ds_write2st64_b32 v186, v0, v119 offset0:1 offset1:17

; __device__ __forceinline__ unsigned cvt_pk_bf16(float lo, float hi) { unsigned r; asm volatile("v_cvt_pk_bf16_f32 %0, %1, %2" : "=v"(r) : "v"(lo), "v"(hi)); return r; }
; __device__ __forceinline__ f32x2 gelu_pk(f32x2 v) {
;     const f32x2 av = __builtin_elementwise_abs(v), d = av * 0.2316418882f + 1.0f;
;     f32x2 t; t.x = __builtin_amdgcn_rcpf(d.x); t.y = __builtin_amdgcn_rcpf(d.y);
;     f32x2 q = t * 0.5307027145f + (-0.7265760135f); q = q * t + 0.7107068705f; q = q * t + (-0.142248368f); q = q * t + 0.127414796f; q = q * t;
;     const f32x2 s = (v * v) * (-0.72134752044f);
;     f32x2 e; e.x = __builtin_amdgcn_exp2f(s.x); e.y = __builtin_amdgcn_exp2f(s.y);
;     const f32x2 m = v * (q * e), r = v - m;
;     f32x2 o; o.x = v.x < 0.f ? m.x : r.x; o.y = v.y < 0.f ? m.y : r.y; return o;
;     __device__ __forceinline__ void operator()(const f32x4 (&acc)[2][2][4][2], const Unit& u, int wr, int wc, int fr, int fq) const {
;     ...
;             for (int m = 0; m < 4; ++m) { const int row = row0 + ai * HALF + m * 16; const float rs = rsv[ai][m]; bf16_t* rowp = O + (size_t)row * ldc + col0; float s1 = 0.f, s2 = 0.f;
; #pragma unroll
;                 for (int bj = 0; bj < 2; ++bj) { f32x4 v0 = acc[ai][bj][m][0] * rs, v1 = acc[ai][bj][m][1] * rs;
;                     const f32x2 a = gelu_pk((f32x2){v0[0], v0[1]}), b = gelu_pk((f32x2){v0[2], v0[3]}), c = gelu_pk((f32x2){v1[0], v1[1]}), d = gelu_pk((f32x2){v1[2], v1[3]});
;                     s1 += ((a.x + a.y) + (b.x + b.y)) + ((c.x + c.y) + (d.x + d.y));
;                     s2 += ((a.x * a.x + a.y * a.y) + (b.x * b.x + b.y * b.y)) + ((c.x * c.x + c.y * c.y) + (d.x * d.x + d.y * d.y));
;                     u32x4 w; w.x = cvt_pk_bf16(a.x, a.y); w.y = cvt_pk_bf16(b.x, b.y); w.z = cvt_pk_bf16(c.x, c.y); w.w = cvt_pk_bf16(d.x, d.y);
;                     *(u32x4*)(rowp + bj * HALF) = w; }
.LBB0_360:
	v_add_f32_e32 v0, v126, v127
	s_waitcnt lgkmcnt(0)
	v_add_f32_e32 v118, v128, v129
	v_add_f32_e32 v0, v0, v118
	v_fmamk_f32 v0, v0, 0x3a800000, v224
	v_rsq_f32_e32 v0, v0
	s_mov_b32 s4, 0xbf3a00e3
	v_lshlrev_b64 v[118:119], 12, v[172:173]
	v_lshl_add_u64 v[118:119], s[20:21], 0, v[118:119]
	v_pk_mul_f32 v[114:115], v[114:115], v[0:1] op_sel_hi:[1,0]
	v_pk_mul_f32 v[120:121], v[106:107], v[0:1] op_sel_hi:[1,0]
	v_and_b32_e32 v107, 0x7fffffff, v115
	v_and_b32_e32 v106, 0x7fffffff, v114
	v_pk_fma_f32 v[106:107], v[106:107], s[64:65], 1.0 op_sel_hi:[1,0,0]
	v_pk_mul_f32 v[126:127], v[114:115], v[114:115]
	v_rcp_f32_e32 v122, v106
	v_rcp_f32_e32 v123, v107
	v_mov_b64_e32 v[106:107], s[4:5]
	v_pk_mul_f32 v[126:127], v[126:127], s[76:77] op_sel_hi:[1,0]
	s_nop 0
	v_pk_fma_f32 v[124:125], v[122:123], s[66:67], v[106:107] op_sel_hi:[1,0,0]
	v_exp_f32_e32 v126, v126
	v_pk_fma_f32 v[124:125], v[122:123], v[124:125], s[70:71] op_sel_hi:[1,1,0]
	v_exp_f32_e32 v127, v127
	v_pk_fma_f32 v[124:125], v[122:123], v[124:125], s[72:73] op_sel_hi:[1,1,0]
	v_pk_mul_f32 v[116:117], v[116:117], v[0:1] op_sel_hi:[1,0]
	v_pk_fma_f32 v[124:125], v[122:123], v[124:125], s[74:75] op_sel_hi:[1,1,0]
	v_pk_mul_f32 v[108:109], v[108:109], v[0:1] op_sel_hi:[1,0]
	v_pk_mul_f32 v[122:123], v[122:123], v[124:125]
	v_pk_mul_f32 v[124:125], v[116:117], v[116:117]
	v_pk_mul_f32 v[122:123], v[126:127], v[122:123]
	v_pk_mul_f32 v[124:125], v[124:125], s[76:77] op_sel_hi:[1,0]
	v_max_f32_e32 v126, 0, v114
	v_max_f32_e32 v127, 0, v115
	v_fma_f32 v114, -|v114|, v122, v126
	v_fma_f32 v115, -|v115|, v123, v127
	v_exp_f32_e32 v124, v124
	s_nop 0
	s_nop 0
	v_and_b32_e32 v122, 0x7fffffff, v116
	v_exp_f32_e32 v125, v125
	s_nop 0
	v_and_b32_e32 v123, 0x7fffffff, v117
	v_pk_fma_f32 v[122:123], v[122:123], s[64:65], 1.0 op_sel_hi:[1,0,0]
	s_nop 0
	v_rcp_f32_e32 v122, v122
	v_rcp_f32_e32 v123, v123
	v_lshl_add_u64 v[118:119], v[160:161], 1, v[118:119]
	v_pk_mul_f32 v[102:103], v[102:103], v[0:1] op_sel_hi:[1,0]
	v_pk_mul_f32 v[104:105], v[104:105], v[0:1] op_sel_hi:[1,0]
	v_pk_fma_f32 v[126:127], v[122:123], s[66:67], v[106:107] op_sel_hi:[1,0,0]
	v_pk_mul_f32 v[100:101], v[100:101], v[0:1] op_sel_hi:[1,0]
	v_pk_fma_f32 v[126:127], v[122:123], v[126:127], s[70:71] op_sel_hi:[1,1,0]
	s_nop 0
	v_pk_fma_f32 v[126:127], v[122:123], v[126:127], s[72:73] op_sel_hi:[1,1,0]
	s_nop 0
	v_pk_fma_f32 v[126:127], v[122:123], v[126:127], s[74:75] op_sel_hi:[1,1,0]
	s_nop 0
	v_pk_mul_f32 v[122:123], v[122:123], v[126:127]
	v_pk_mul_f32 v[126:127], v[120:121], v[120:121]
	v_pk_mul_f32 v[122:123], v[124:125], v[122:123]
	v_pk_mul_f32 v[126:127], v[126:127], s[76:77] op_sel_hi:[1,0]
	v_max_f32_e32 v124, 0, v116
	v_max_f32_e32 v125, 0, v117
	v_fma_f32 v116, -|v116|, v122, v124
	v_fma_f32 v117, -|v117|, v123, v125
	v_exp_f32_e32 v126, v126
	s_nop 0
	s_nop 0
	v_and_b32_e32 v122, 0x7fffffff, v120
	v_exp_f32_e32 v127, v127
	s_nop 0
	v_and_b32_e32 v123, 0x7fffffff, v121
	v_pk_fma_f32 v[122:123], v[122:123], s[64:65], 1.0 op_sel_hi:[1,0,0]
	s_nop 0
	v_rcp_f32_e32 v122, v122
	v_rcp_f32_e32 v123, v123
	s_nop 0
	v_pk_fma_f32 v[124:125], v[122:123], s[66:67], v[106:107] op_sel_hi:[1,0,0]
	s_nop 0
	v_pk_fma_f32 v[124:125], v[122:123], v[124:125], s[70:71] op_sel_hi:[1,1,0]
	s_nop 0
	v_pk_fma_f32 v[124:125], v[122:123], v[124:125], s[72:73] op_sel_hi:[1,1,0]
	s_nop 0
	v_pk_fma_f32 v[124:125], v[122:123], v[124:125], s[74:75] op_sel_hi:[1,1,0]
	s_nop 0
	v_pk_mul_f32 v[122:123], v[122:123], v[124:125]
	v_pk_mul_f32 v[124:125], v[108:109], v[108:109]
	v_pk_mul_f32 v[122:123], v[126:127], v[122:123]
	v_pk_mul_f32 v[124:125], v[124:125], s[76:77] op_sel_hi:[1,0]
	v_max_f32_e32 v126, 0, v120
	v_max_f32_e32 v127, 0, v121
	v_fma_f32 v120, -|v120|, v122, v126
	v_fma_f32 v121, -|v121|, v123, v127
	v_exp_f32_e32 v124, v124
	s_nop 0
	s_nop 0
	v_and_b32_e32 v122, 0x7fffffff, v108
	v_exp_f32_e32 v125, v125
	s_nop 0
	v_and_b32_e32 v123, 0x7fffffff, v109
	v_pk_fma_f32 v[122:123], v[122:123], s[64:65], 1.0 op_sel_hi:[1,0,0]
	s_nop 0
	v_rcp_f32_e32 v122, v122
	v_rcp_f32_e32 v123, v123
	s_nop 0
	v_pk_fma_f32 v[126:127], v[122:123], s[66:67], v[106:107] op_sel_hi:[1,0,0]
	s_nop 0
	v_pk_fma_f32 v[126:127], v[122:123], v[126:127], s[70:71] op_sel_hi:[1,1,0]
	s_nop 0
	v_pk_fma_f32 v[126:127], v[122:123], v[126:127], s[72:73] op_sel_hi:[1,1,0]
	s_nop 0
	v_pk_fma_f32 v[126:127], v[122:123], v[126:127], s[74:75] op_sel_hi:[1,1,0]
	s_nop 0
	v_pk_mul_f32 v[122:123], v[122:123], v[126:127]
	v_pk_mul_f32 v[126:127], v[102:103], v[102:103]
	v_pk_mul_f32 v[122:123], v[124:125], v[122:123]
	v_pk_mul_f32 v[126:127], v[126:127], s[76:77] op_sel_hi:[1,0]
	v_max_f32_e32 v124, 0, v108
	v_max_f32_e32 v125, 0, v109
	v_fma_f32 v108, -|v108|, v122, v124
	v_fma_f32 v109, -|v109|, v123, v125
	v_exp_f32_e32 v126, v126
	s_nop 0
	s_nop 0
	v_cvt_pk_bf16_f32 v122, v114, v115
	v_exp_f32_e32 v127, v127
	s_nop 0
	s_nop 0
	v_cvt_pk_bf16_f32 v123, v116, v117
	v_cvt_pk_bf16_f32 v124, v120, v121
	v_cvt_pk_bf16_f32 v125, v108, v109
	global_store_dwordx4 v[118:119], v[122:125], off
	s_nop 0
	s_nop 0
	v_pk_mul_f32 v[122:123], v[98:99], v[0:1] op_sel_hi:[1,0]
	v_and_b32_e32 v99, 0x7fffffff, v103
	v_and_b32_e32 v98, 0x7fffffff, v102
	v_pk_fma_f32 v[98:99], v[98:99], s[64:65], 1.0 op_sel_hi:[1,0,0]
	s_nop 0
	v_rcp_f32_e32 v98, v98
	v_rcp_f32_e32 v99, v99
	s_nop 0
	v_pk_fma_f32 v[124:125], v[98:99], s[66:67], v[106:107] op_sel_hi:[1,0,0]
	s_nop 0
	v_pk_fma_f32 v[124:125], v[98:99], v[124:125], s[70:71] op_sel_hi:[1,1,0]
	s_nop 0
	v_pk_fma_f32 v[124:125], v[98:99], v[124:125], s[72:73] op_sel_hi:[1,1,0]
	s_nop 0
	v_pk_fma_f32 v[124:125], v[98:99], v[124:125], s[74:75] op_sel_hi:[1,1,0]
; __device__ __forceinline__ unsigned cvt_pk_bf16(float lo, float hi) { unsigned r; asm volatile("v_cvt_pk_bf16_f32 %0, %1, %2" : "=v"(r) : "v"(lo), "v"(hi)); return r; }
; __device__ __forceinline__ f32x2 gelu_pk(f32x2 v) {
;     const f32x2 av = __builtin_elementwise_abs(v), d = av * 0.2316418882f + 1.0f;
;     f32x2 t; t.x = __builtin_amdgcn_rcpf(d.x); t.y = __builtin_amdgcn_rcpf(d.y);
;     f32x2 q = t * 0.5307027145f + (-0.7265760135f); q = q * t + 0.7107068705f; q = q * t + (-0.142248368f); q = q * t + 0.127414796f; q = q * t;
;     const f32x2 s = (v * v) * (-0.72134752044f);
;     f32x2 e; e.x = __builtin_amdgcn_exp2f(s.x); e.y = __builtin_amdgcn_exp2f(s.y);
;     const f32x2 m = v * (q * e), r = v - m;
;     f32x2 o; o.x = v.x < 0.f ? m.x : r.x; o.y = v.y < 0.f ? m.y : r.y; return o;
; }
;     __device__ __forceinline__ void operator()(const f32x4 (&acc)[2][2][4][2], const Unit& u, int wr, int wc, int fr, int fq) const {
;     ...
;                 for (int bj = 0; bj < 2; ++bj) { f32x4 v0 = acc[ai][bj][m][0] * rs, v1 = acc[ai][bj][m][1] * rs;
;                     const f32x2 a = gelu_pk((f32x2){v0[0], v0[1]}), b = gelu_pk((f32x2){v0[2], v0[3]}), c = gelu_pk((f32x2){v1[0], v1[1]}), d = gelu_pk((f32x2){v1[2], v1[3]});
;                     s1 += ((a.x + a.y) + (b.x + b.y)) + ((c.x + c.y) + (d.x + d.y));
;                     s2 += ((a.x * a.x + a.y * a.y) + (b.x * b.x + b.y * b.y)) + ((c.x * c.x + c.y * c.y) + (d.x * d.x + d.y * d.y));
;                     u32x4 w; w.x = cvt_pk_bf16(a.x, a.y); w.y = cvt_pk_bf16(b.x, b.y); w.z = cvt_pk_bf16(c.x, c.y); w.w = cvt_pk_bf16(d.x, d.y);
;                     *(u32x4*)(rowp + bj * HALF) = w; }
;                 if (isv) { s1 += __shfl_xor(s1, 16); s1 += __shfl_xor(s1, 32); s2 += __shfl_xor(s2, 16); s2 += __shfl_xor(s2, 32);
;                     if (fq == 0) { const int rl = ai * HALF + wr * 64 + m * 16 + fr; part[rl * 4 + wc] = s1; part[1024 + rl * 4 + wc] = s2; } } }
	s_nop 0
	v_pk_mul_f32 v[98:99], v[98:99], v[124:125]
	v_pk_mul_f32 v[124:125], v[104:105], v[104:105]
	v_pk_mul_f32 v[98:99], v[126:127], v[98:99]
	v_pk_mul_f32 v[124:125], v[124:125], s[76:77] op_sel_hi:[1,0]
	v_max_f32_e32 v126, 0, v102
	v_max_f32_e32 v127, 0, v103
	v_fma_f32 v0, -|v102|, v98, v126
	v_fma_f32 v98, -|v103|, v99, v127
	v_and_b32_e32 v102, 0x7fffffff, v104
	s_nop 0
	s_nop 0
	v_and_b32_e32 v103, 0x7fffffff, v105
	v_pk_fma_f32 v[102:103], v[102:103], s[64:65], 1.0 op_sel_hi:[1,0,0]
	s_nop 0
	v_rcp_f32_e32 v102, v102
	v_rcp_f32_e32 v103, v103
	v_exp_f32_e32 v124, v124
	v_exp_f32_e32 v125, v125
	s_nop 0
	v_pk_fma_f32 v[126:127], v[102:103], s[66:67], v[106:107] op_sel_hi:[1,0,0]
	s_nop 0
	v_pk_fma_f32 v[126:127], v[102:103], v[126:127], s[70:71] op_sel_hi:[1,1,0]
	s_nop 0
	v_pk_fma_f32 v[126:127], v[102:103], v[126:127], s[72:73] op_sel_hi:[1,1,0]
	s_nop 0
	v_pk_fma_f32 v[126:127], v[102:103], v[126:127], s[74:75] op_sel_hi:[1,1,0]
	s_nop 0
	v_pk_mul_f32 v[102:103], v[102:103], v[126:127]
	v_pk_mul_f32 v[126:127], v[122:123], v[122:123]
	v_pk_mul_f32 v[102:103], v[124:125], v[102:103]
	v_pk_mul_f32 v[126:127], v[126:127], s[76:77] op_sel_hi:[1,0]
	v_max_f32_e32 v124, 0, v104
	v_max_f32_e32 v125, 0, v105
	v_fma_f32 v99, -|v104|, v102, v124
	v_fma_f32 v102, -|v105|, v103, v125
	v_and_b32_e32 v104, 0x7fffffff, v122
	s_nop 0
	s_nop 0
	v_and_b32_e32 v105, 0x7fffffff, v123
	v_pk_fma_f32 v[104:105], v[104:105], s[64:65], 1.0 op_sel_hi:[1,0,0]
	s_nop 0
	v_rcp_f32_e32 v104, v104
	v_rcp_f32_e32 v105, v105
	v_exp_f32_e32 v126, v126
	v_exp_f32_e32 v127, v127
	s_nop 0
	v_pk_fma_f32 v[124:125], v[104:105], s[66:67], v[106:107] op_sel_hi:[1,0,0]
	s_nop 0
	v_pk_fma_f32 v[124:125], v[104:105], v[124:125], s[70:71] op_sel_hi:[1,1,0]
	s_nop 0
	v_pk_fma_f32 v[124:125], v[104:105], v[124:125], s[72:73] op_sel_hi:[1,1,0]
	s_nop 0
	v_pk_fma_f32 v[124:125], v[104:105], v[124:125], s[74:75] op_sel_hi:[1,1,0]
	s_nop 0
	v_pk_mul_f32 v[104:105], v[104:105], v[124:125]
	v_pk_mul_f32 v[124:125], v[100:101], v[100:101]
	v_pk_mul_f32 v[104:105], v[126:127], v[104:105]
	s_nop 0
	v_max_f32_e32 v126, 0, v122
	v_max_f32_e32 v127, 0, v123
	v_fma_f32 v103, -|v122|, v104, v126
	v_fma_f32 v104, -|v123|, v105, v127
	v_and_b32_e32 v122, 0x7fffffff, v100
	s_nop 0
	s_nop 0
	v_and_b32_e32 v123, 0x7fffffff, v101
	v_pk_fma_f32 v[122:123], v[122:123], s[64:65], 1.0 op_sel_hi:[1,0,0]
	s_nop 0
	v_rcp_f32_e32 v122, v122
	v_rcp_f32_e32 v123, v123
	s_nop 0
	v_pk_fma_f32 v[106:107], v[122:123], s[66:67], v[106:107] op_sel_hi:[1,0,0]
	s_nop 0
	v_pk_fma_f32 v[106:107], v[122:123], v[106:107], s[70:71] op_sel_hi:[1,1,0]
	s_nop 0
	v_pk_fma_f32 v[106:107], v[122:123], v[106:107], s[72:73] op_sel_hi:[1,1,0]
	s_nop 0
	v_pk_fma_f32 v[106:107], v[122:123], v[106:107], s[74:75] op_sel_hi:[1,1,0]
	s_nop 0
	v_pk_mul_f32 v[106:107], v[122:123], v[106:107]
	v_pk_mul_f32 v[122:123], v[124:125], s[76:77] op_sel_hi:[1,0]
	s_nop 0
	v_exp_f32_e32 v122, v122
	v_exp_f32_e32 v123, v123
	s_nop 0
	v_pk_mul_f32 v[106:107], v[122:123], v[106:107]
	s_nop 0
	v_max_f32_e32 v122, 0, v100
	v_max_f32_e32 v123, 0, v101
	v_fma_f32 v100, -|v100|, v106, v122
	v_fma_f32 v101, -|v101|, v107, v123
	s_nop 0
	s_nop 0
	s_nop 0
	v_cvt_pk_bf16_f32 v122, v0, v98
	s_nop 1
	s_nop 0
	s_and_b64 vcc, exec, s[10:11]
	v_cvt_pk_bf16_f32 v123, v99, v102
	v_cvt_pk_bf16_f32 v124, v103, v104
	v_cvt_pk_bf16_f32 v125, v100, v101
	global_store_dwordx4 v[118:119], v[122:125], off offset:256
	s_cbranch_vccnz .LBB0_364
	v_mul_f32_e32 v105, v115, v115
	v_mul_f32_e32 v106, v117, v117
	v_fmac_f32_e32 v105, v114, v114
	v_fmac_f32_e32 v106, v116, v116
	v_add_f32_e32 v105, v105, v106
	v_mul_f32_e32 v106, v121, v121
	v_mul_f32_e32 v107, v109, v109
	v_fmac_f32_e32 v106, v120, v120
	v_fmac_f32_e32 v107, v108, v108
	v_add_f32_e32 v106, v106, v107
	v_add_f32_e32 v105, v105, v106
	v_mul_f32_e32 v106, v98, v98
	v_fmac_f32_e32 v106, v0, v0
	v_mul_f32_e32 v107, v102, v102
	v_add_f32_e32 v0, v0, v98
	v_add_f32_e32 v98, v99, v102
	v_fmac_f32_e32 v107, v99, v99
	v_add_f32_e32 v114, v114, v115
	v_add_f32_e32 v115, v116, v117
	v_add_f32_e32 v0, v0, v98
	v_add_f32_e32 v98, v103, v104
	v_add_f32_e32 v99, v100, v101
	v_add_f32_e32 v114, v114, v115
	v_add_f32_e32 v115, v120, v121
	v_add_f32_e32 v108, v108, v109
	v_add_f32_e32 v98, v98, v99
	v_and_b32_e32 v99, 64, v226
	v_add_f32_e32 v108, v115, v108
	v_add_f32_e32 v0, v0, v98
	v_xor_b32_e32 v98, 16, v226
	v_add_u32_e32 v99, 64, v99
	v_add_f32_e32 v108, v114, v108
	v_cmp_lt_i32_e32 vcc, v98, v99
	v_add_f32_e32 v106, v106, v107
	v_mul_f32_e32 v107, v104, v104
	v_mul_f32_e32 v118, v101, v101
	v_add_f32_e32 v108, 0, v108
	v_cndmask_b32_e32 v98, v226, v98, vcc
	v_fmac_f32_e32 v107, v103, v103
	v_add_f32_e32 v0, v0, v108
	v_lshlrev_b32_e32 v98, 2, v98
	v_fmac_f32_e32 v118, v100, v100
	v_mov_b32_e32 v101, v0
	s_nop 1
	v_permlane16_swap_b32_e32 v101, v0
	v_add_f32_e32 v100, v107, v118
	v_add_f32_e32 v100, v106, v100
	v_add_f32_e32 v100, v105, v100
	v_mov_b32_e32 v102, v100
	s_nop 1
	v_permlane16_swap_b32_e32 v102, v100
	s_waitcnt lgkmcnt(0)
	v_add_f32_e32 v0, v0, v101
	v_xor_b32_e32 v101, 32, v226
	v_cmp_lt_i32_e32 vcc, v101, v99
	v_add_f32_e32 v99, v100, v102
	s_nop 0
	v_cndmask_b32_e32 v98, v226, v101, vcc
	v_lshlrev_b32_e32 v101, 2, v98
	v_mov_b32_e32 v98, v0
	s_nop 1
	v_permlane32_swap_b32_e32 v98, v0
	v_mov_b32_e32 v100, v99
	s_nop 1
	v_permlane32_swap_b32_e32 v100, v99
	s_and_saveexec_b64 s[4:5], s[6:7]
	s_cbranch_execz .LBB0_363
	s_waitcnt lgkmcnt(0)
	v_add_f32_e32 v99, v99, v100
	v_add_f32_e32 v0, v0, v98
	ds_write2st64_b32 v186, v0, v99 offset0:2 offset1:18

; __device__ __forceinline__ unsigned cvt_pk_bf16(float lo, float hi) { unsigned r; asm volatile("v_cvt_pk_bf16_f32 %0, %1, %2" : "=v"(r) : "v"(lo), "v"(hi)); return r; }
; __device__ __forceinline__ f32x2 gelu_pk(f32x2 v) {
;     const f32x2 av = __builtin_elementwise_abs(v), d = av * 0.2316418882f + 1.0f;
;     f32x2 t; t.x = __builtin_amdgcn_rcpf(d.x); t.y = __builtin_amdgcn_rcpf(d.y);
;     f32x2 q = t * 0.5307027145f + (-0.7265760135f); q = q * t + 0.7107068705f; q = q * t + (-0.142248368f); q = q * t + 0.127414796f; q = q * t;
;     const f32x2 s = (v * v) * (-0.72134752044f);
;     f32x2 e; e.x = __builtin_amdgcn_exp2f(s.x); e.y = __builtin_amdgcn_exp2f(s.y);
;     const f32x2 m = v * (q * e), r = v - m;
;     f32x2 o; o.x = v.x < 0.f ? m.x : r.x; o.y = v.y < 0.f ? m.y : r.y; return o;
; }
;     __device__ __forceinline__ void operator()(const f32x4 (&acc)[2][2][4][2], const Unit& u, int wr, int wc, int fr, int fq) const {
;     ...
;             for (int m = 0; m < 4; ++m) { const int row = row0 + ai * HALF + m * 16; const float rs = rsv[ai][m]; bf16_t* rowp = O + (size_t)row * ldc + col0; float s1 = 0.f, s2 = 0.f;
; #pragma unroll
;                 for (int bj = 0; bj < 2; ++bj) { f32x4 v0 = acc[ai][bj][m][0] * rs, v1 = acc[ai][bj][m][1] * rs;
;                     const f32x2 a = gelu_pk((f32x2){v0[0], v0[1]}), b = gelu_pk((f32x2){v0[2], v0[3]}), c = gelu_pk((f32x2){v1[0], v1[1]}), d = gelu_pk((f32x2){v1[2], v1[3]});
;                     s1 += ((a.x + a.y) + (b.x + b.y)) + ((c.x + c.y) + (d.x + d.y));
;                     s2 += ((a.x * a.x + a.y * a.y) + (b.x * b.x + b.y * b.y)) + ((c.x * c.x + c.y * c.y) + (d.x * d.x + d.y * d.y));
;                     u32x4 w; w.x = cvt_pk_bf16(a.x, a.y); w.y = cvt_pk_bf16(b.x, b.y); w.z = cvt_pk_bf16(c.x, c.y); w.w = cvt_pk_bf16(d.x, d.y);
;                     *(u32x4*)(rowp + bj * HALF) = w; }
.LBB0_364:
	v_add_f32_e32 v0, v110, v111
	s_waitcnt lgkmcnt(0)
	v_add_f32_e32 v98, v112, v113
	v_add_f32_e32 v0, v0, v98
	v_fmamk_f32 v0, v0, 0x3a800000, v224
	v_rsq_f32_e32 v0, v0
	s_mov_b32 s4, 0xbf3a00e3
	v_lshlrev_b64 v[98:99], 12, v[170:171]
	v_lshl_add_u64 v[98:99], s[20:21], 0, v[98:99]
	v_pk_mul_f32 v[90:91], v[90:91], v[0:1] op_sel_hi:[1,0]
	v_pk_mul_f32 v[100:101], v[86:87], v[0:1] op_sel_hi:[1,0]
	v_and_b32_e32 v87, 0x7fffffff, v91
	v_and_b32_e32 v86, 0x7fffffff, v90
	v_pk_fma_f32 v[86:87], v[86:87], s[64:65], 1.0 op_sel_hi:[1,0,0]
	v_pk_mul_f32 v[106:107], v[90:91], v[90:91]
	v_rcp_f32_e32 v102, v86
	v_rcp_f32_e32 v103, v87
	v_mov_b64_e32 v[86:87], s[4:5]
	v_pk_mul_f32 v[106:107], v[106:107], s[76:77] op_sel_hi:[1,0]
	s_nop 0
	v_pk_fma_f32 v[104:105], v[102:103], s[66:67], v[86:87] op_sel_hi:[1,0,0]
	v_exp_f32_e32 v106, v106
	v_pk_fma_f32 v[104:105], v[102:103], v[104:105], s[70:71] op_sel_hi:[1,1,0]
	v_exp_f32_e32 v107, v107
	v_pk_fma_f32 v[104:105], v[102:103], v[104:105], s[72:73] op_sel_hi:[1,1,0]
	v_pk_mul_f32 v[92:93], v[92:93], v[0:1] op_sel_hi:[1,0]
	v_pk_fma_f32 v[104:105], v[102:103], v[104:105], s[74:75] op_sel_hi:[1,1,0]
	v_pk_mul_f32 v[88:89], v[88:89], v[0:1] op_sel_hi:[1,0]
	v_pk_mul_f32 v[102:103], v[102:103], v[104:105]
	v_pk_mul_f32 v[104:105], v[92:93], v[92:93]
	v_pk_mul_f32 v[102:103], v[106:107], v[102:103]
	v_pk_mul_f32 v[104:105], v[104:105], s[76:77] op_sel_hi:[1,0]
	v_max_f32_e32 v106, 0, v90
	v_max_f32_e32 v107, 0, v91
	v_fma_f32 v90, -|v90|, v102, v106
	v_fma_f32 v91, -|v91|, v103, v107
	v_exp_f32_e32 v104, v104
	s_nop 0
	s_nop 0
	v_and_b32_e32 v102, 0x7fffffff, v92
	v_exp_f32_e32 v105, v105
	s_nop 0
	v_and_b32_e32 v103, 0x7fffffff, v93
	v_pk_fma_f32 v[102:103], v[102:103], s[64:65], 1.0 op_sel_hi:[1,0,0]
	s_nop 0
	v_rcp_f32_e32 v102, v102
	v_rcp_f32_e32 v103, v103
	v_lshl_add_u64 v[98:99], v[160:161], 1, v[98:99]
	v_pk_mul_f32 v[82:83], v[82:83], v[0:1] op_sel_hi:[1,0]
	v_pk_mul_f32 v[84:85], v[84:85], v[0:1] op_sel_hi:[1,0]
	v_pk_fma_f32 v[106:107], v[102:103], s[66:67], v[86:87] op_sel_hi:[1,0,0]
	v_pk_mul_f32 v[80:81], v[80:81], v[0:1] op_sel_hi:[1,0]
	v_pk_fma_f32 v[106:107], v[102:103], v[106:107], s[70:71] op_sel_hi:[1,1,0]
	s_nop 0
	v_pk_fma_f32 v[106:107], v[102:103], v[106:107], s[72:73] op_sel_hi:[1,1,0]
	s_nop 0
	v_pk_fma_f32 v[106:107], v[102:103], v[106:107], s[74:75] op_sel_hi:[1,1,0]
	s_nop 0
	v_pk_mul_f32 v[102:103], v[102:103], v[106:107]
	v_pk_mul_f32 v[106:107], v[100:101], v[100:101]
	v_pk_mul_f32 v[102:103], v[104:105], v[102:103]
	v_pk_mul_f32 v[106:107], v[106:107], s[76:77] op_sel_hi:[1,0]
	v_max_f32_e32 v104, 0, v92
	v_max_f32_e32 v105, 0, v93
	v_fma_f32 v92, -|v92|, v102, v104
	v_fma_f32 v93, -|v93|, v103, v105
	v_exp_f32_e32 v106, v106
	s_nop 0
	s_nop 0
	v_and_b32_e32 v102, 0x7fffffff, v100
	v_exp_f32_e32 v107, v107
	s_nop 0
	v_and_b32_e32 v103, 0x7fffffff, v101
	v_pk_fma_f32 v[102:103], v[102:103], s[64:65], 1.0 op_sel_hi:[1,0,0]
	s_nop 0
	v_rcp_f32_e32 v102, v102
	v_rcp_f32_e32 v103, v103
	s_nop 0
	v_pk_fma_f32 v[104:105], v[102:103], s[66:67], v[86:87] op_sel_hi:[1,0,0]
	s_nop 0
	v_pk_fma_f32 v[104:105], v[102:103], v[104:105], s[70:71] op_sel_hi:[1,1,0]
	s_nop 0
	v_pk_fma_f32 v[104:105], v[102:103], v[104:105], s[72:73] op_sel_hi:[1,1,0]
	s_nop 0
	v_pk_fma_f32 v[104:105], v[102:103], v[104:105], s[74:75] op_sel_hi:[1,1,0]
	s_nop 0
	v_pk_mul_f32 v[102:103], v[102:103], v[104:105]
	v_pk_mul_f32 v[104:105], v[88:89], v[88:89]
	v_pk_mul_f32 v[102:103], v[106:107], v[102:103]
	v_pk_mul_f32 v[104:105], v[104:105], s[76:77] op_sel_hi:[1,0]
	v_max_f32_e32 v106, 0, v100
	v_max_f32_e32 v107, 0, v101
	v_fma_f32 v100, -|v100|, v102, v106
	v_fma_f32 v101, -|v101|, v103, v107
	v_exp_f32_e32 v104, v104
	s_nop 0
	s_nop 0
	v_and_b32_e32 v102, 0x7fffffff, v88
	v_exp_f32_e32 v105, v105
	s_nop 0
	v_and_b32_e32 v103, 0x7fffffff, v89
	v_pk_fma_f32 v[102:103], v[102:103], s[64:65], 1.0 op_sel_hi:[1,0,0]
	s_nop 0
	v_rcp_f32_e32 v102, v102
	v_rcp_f32_e32 v103, v103
	s_nop 0
	v_pk_fma_f32 v[106:107], v[102:103], s[66:67], v[86:87] op_sel_hi:[1,0,0]
	s_nop 0
	v_pk_fma_f32 v[106:107], v[102:103], v[106:107], s[70:71] op_sel_hi:[1,1,0]
	s_nop 0
	v_pk_fma_f32 v[106:107], v[102:103], v[106:107], s[72:73] op_sel_hi:[1,1,0]
	s_nop 0
	v_pk_fma_f32 v[106:107], v[102:103], v[106:107], s[74:75] op_sel_hi:[1,1,0]
	s_nop 0
	v_pk_mul_f32 v[102:103], v[102:103], v[106:107]
	v_pk_mul_f32 v[106:107], v[82:83], v[82:83]
	v_pk_mul_f32 v[102:103], v[104:105], v[102:103]
	v_pk_mul_f32 v[106:107], v[106:107], s[76:77] op_sel_hi:[1,0]
	v_max_f32_e32 v104, 0, v88
	v_max_f32_e32 v105, 0, v89
	v_fma_f32 v88, -|v88|, v102, v104
	v_fma_f32 v89, -|v89|, v103, v105
	v_exp_f32_e32 v106, v106
	s_nop 0
	s_nop 0
	v_cvt_pk_bf16_f32 v102, v90, v91
	v_exp_f32_e32 v107, v107
	s_nop 0
	s_nop 0
	v_cvt_pk_bf16_f32 v103, v92, v93
	v_cvt_pk_bf16_f32 v104, v100, v101
	v_cvt_pk_bf16_f32 v105, v88, v89
	global_store_dwordx4 v[98:99], v[102:105], off
	s_nop 0
	s_nop 0
	v_pk_mul_f32 v[102:103], v[78:79], v[0:1] op_sel_hi:[1,0]
	v_and_b32_e32 v79, 0x7fffffff, v83
	v_and_b32_e32 v78, 0x7fffffff, v82
	v_pk_fma_f32 v[78:79], v[78:79], s[64:65], 1.0 op_sel_hi:[1,0,0]
	s_nop 0
	v_rcp_f32_e32 v78, v78
	v_rcp_f32_e32 v79, v79
	s_nop 0
	v_pk_fma_f32 v[104:105], v[78:79], s[66:67], v[86:87] op_sel_hi:[1,0,0]
	s_nop 0
	v_pk_fma_f32 v[104:105], v[78:79], v[104:105], s[70:71] op_sel_hi:[1,1,0]
	s_nop 0
	v_pk_fma_f32 v[104:105], v[78:79], v[104:105], s[72:73] op_sel_hi:[1,1,0]
; __device__ __forceinline__ unsigned cvt_pk_bf16(float lo, float hi) { unsigned r; asm volatile("v_cvt_pk_bf16_f32 %0, %1, %2" : "=v"(r) : "v"(lo), "v"(hi)); return r; }
; __device__ __forceinline__ f32x2 gelu_pk(f32x2 v) {
;     const f32x2 av = __builtin_elementwise_abs(v), d = av * 0.2316418882f + 1.0f;
;     f32x2 t; t.x = __builtin_amdgcn_rcpf(d.x); t.y = __builtin_amdgcn_rcpf(d.y);
;     f32x2 q = t * 0.5307027145f + (-0.7265760135f); q = q * t + 0.7107068705f; q = q * t + (-0.142248368f); q = q * t + 0.127414796f; q = q * t;
;     const f32x2 s = (v * v) * (-0.72134752044f);
;     f32x2 e; e.x = __builtin_amdgcn_exp2f(s.x); e.y = __builtin_amdgcn_exp2f(s.y);
;     const f32x2 m = v * (q * e), r = v - m;
;     f32x2 o; o.x = v.x < 0.f ? m.x : r.x; o.y = v.y < 0.f ? m.y : r.y; return o;
; }
;     __device__ __forceinline__ void operator()(const f32x4 (&acc)[2][2][4][2], const Unit& u, int wr, int wc, int fr, int fq) const {
;     ...
;                 for (int bj = 0; bj < 2; ++bj) { f32x4 v0 = acc[ai][bj][m][0] * rs, v1 = acc[ai][bj][m][1] * rs;
;                     const f32x2 a = gelu_pk((f32x2){v0[0], v0[1]}), b = gelu_pk((f32x2){v0[2], v0[3]}), c = gelu_pk((f32x2){v1[0], v1[1]}), d = gelu_pk((f32x2){v1[2], v1[3]});
;                     s1 += ((a.x + a.y) + (b.x + b.y)) + ((c.x + c.y) + (d.x + d.y));
;                     s2 += ((a.x * a.x + a.y * a.y) + (b.x * b.x + b.y * b.y)) + ((c.x * c.x + c.y * c.y) + (d.x * d.x + d.y * d.y));
;                     u32x4 w; w.x = cvt_pk_bf16(a.x, a.y); w.y = cvt_pk_bf16(b.x, b.y); w.z = cvt_pk_bf16(c.x, c.y); w.w = cvt_pk_bf16(d.x, d.y);
;                     *(u32x4*)(rowp + bj * HALF) = w; }
;                 if (isv) { s1 += __shfl_xor(s1, 16); s1 += __shfl_xor(s1, 32); s2 += __shfl_xor(s2, 16); s2 += __shfl_xor(s2, 32);
;                     if (fq == 0) { const int rl = ai * HALF + wr * 64 + m * 16 + fr; part[rl * 4 + wc] = s1; part[1024 + rl * 4 + wc] = s2; } } }
	s_nop 0
	v_pk_fma_f32 v[104:105], v[78:79], v[104:105], s[74:75] op_sel_hi:[1,1,0]
	s_nop 0
	v_pk_mul_f32 v[78:79], v[78:79], v[104:105]
	v_pk_mul_f32 v[104:105], v[84:85], v[84:85]
	v_pk_mul_f32 v[78:79], v[106:107], v[78:79]
	v_pk_mul_f32 v[104:105], v[104:105], s[76:77] op_sel_hi:[1,0]
	v_max_f32_e32 v106, 0, v82
	v_max_f32_e32 v107, 0, v83
	v_fma_f32 v0, -|v82|, v78, v106
	v_fma_f32 v78, -|v83|, v79, v107
	v_and_b32_e32 v82, 0x7fffffff, v84
	s_nop 0
	s_nop 0
	v_and_b32_e32 v83, 0x7fffffff, v85
	v_pk_fma_f32 v[82:83], v[82:83], s[64:65], 1.0 op_sel_hi:[1,0,0]
	s_nop 0
	v_rcp_f32_e32 v82, v82
	v_rcp_f32_e32 v83, v83
	v_exp_f32_e32 v104, v104
	v_exp_f32_e32 v105, v105
	s_nop 0
	v_pk_fma_f32 v[106:107], v[82:83], s[66:67], v[86:87] op_sel_hi:[1,0,0]
	s_nop 0
	v_pk_fma_f32 v[106:107], v[82:83], v[106:107], s[70:71] op_sel_hi:[1,1,0]
	s_nop 0
	v_pk_fma_f32 v[106:107], v[82:83], v[106:107], s[72:73] op_sel_hi:[1,1,0]
	s_nop 0
	v_pk_fma_f32 v[106:107], v[82:83], v[106:107], s[74:75] op_sel_hi:[1,1,0]
	s_nop 0
	v_pk_mul_f32 v[82:83], v[82:83], v[106:107]
	v_pk_mul_f32 v[106:107], v[102:103], v[102:103]
	v_pk_mul_f32 v[82:83], v[104:105], v[82:83]
	v_pk_mul_f32 v[106:107], v[106:107], s[76:77] op_sel_hi:[1,0]
	v_max_f32_e32 v104, 0, v84
	v_max_f32_e32 v105, 0, v85
	v_fma_f32 v79, -|v84|, v82, v104
	v_fma_f32 v82, -|v85|, v83, v105
	v_and_b32_e32 v84, 0x7fffffff, v102
	s_nop 0
	s_nop 0
	v_and_b32_e32 v85, 0x7fffffff, v103
	v_pk_fma_f32 v[84:85], v[84:85], s[64:65], 1.0 op_sel_hi:[1,0,0]
	s_nop 0
	v_rcp_f32_e32 v84, v84
	v_rcp_f32_e32 v85, v85
	v_exp_f32_e32 v106, v106
	v_exp_f32_e32 v107, v107
	s_nop 0
	v_pk_fma_f32 v[104:105], v[84:85], s[66:67], v[86:87] op_sel_hi:[1,0,0]
	s_nop 0
	v_pk_fma_f32 v[104:105], v[84:85], v[104:105], s[70:71] op_sel_hi:[1,1,0]
	s_nop 0
	v_pk_fma_f32 v[104:105], v[84:85], v[104:105], s[72:73] op_sel_hi:[1,1,0]
	s_nop 0
	v_pk_fma_f32 v[104:105], v[84:85], v[104:105], s[74:75] op_sel_hi:[1,1,0]
	s_nop 0
	v_pk_mul_f32 v[84:85], v[84:85], v[104:105]
	v_pk_mul_f32 v[104:105], v[80:81], v[80:81]
	v_pk_mul_f32 v[84:85], v[106:107], v[84:85]
	s_nop 0
	v_max_f32_e32 v106, 0, v102
	v_max_f32_e32 v107, 0, v103
	v_fma_f32 v83, -|v102|, v84, v106
	v_fma_f32 v84, -|v103|, v85, v107
	v_and_b32_e32 v102, 0x7fffffff, v80
	s_nop 0
	s_nop 0
	v_and_b32_e32 v103, 0x7fffffff, v81
	v_pk_fma_f32 v[102:103], v[102:103], s[64:65], 1.0 op_sel_hi:[1,0,0]
	s_nop 0
	v_rcp_f32_e32 v102, v102
	v_rcp_f32_e32 v103, v103
	s_nop 0
	v_pk_fma_f32 v[86:87], v[102:103], s[66:67], v[86:87] op_sel_hi:[1,0,0]
	s_nop 0
	v_pk_fma_f32 v[86:87], v[102:103], v[86:87], s[70:71] op_sel_hi:[1,1,0]
	s_nop 0
	v_pk_fma_f32 v[86:87], v[102:103], v[86:87], s[72:73] op_sel_hi:[1,1,0]
	s_nop 0
	v_pk_fma_f32 v[86:87], v[102:103], v[86:87], s[74:75] op_sel_hi:[1,1,0]
	s_nop 0
	v_pk_mul_f32 v[86:87], v[102:103], v[86:87]
	v_pk_mul_f32 v[102:103], v[104:105], s[76:77] op_sel_hi:[1,0]
	s_nop 0
	v_exp_f32_e32 v102, v102
	v_exp_f32_e32 v103, v103
	s_nop 0
	v_pk_mul_f32 v[86:87], v[102:103], v[86:87]
	s_nop 0
	v_max_f32_e32 v102, 0, v80
	v_max_f32_e32 v103, 0, v81
	v_fma_f32 v80, -|v80|, v86, v102
	v_fma_f32 v81, -|v81|, v87, v103
	s_nop 0
	s_nop 0
	s_nop 0
	v_cvt_pk_bf16_f32 v102, v0, v78
	s_nop 1
	s_nop 0
	s_and_b64 vcc, exec, s[10:11]
	v_cvt_pk_bf16_f32 v103, v79, v82
	v_cvt_pk_bf16_f32 v104, v83, v84
	v_cvt_pk_bf16_f32 v105, v80, v81
	global_store_dwordx4 v[98:99], v[102:105], off offset:256
	s_cbranch_vccnz .LBB0_368
	v_mul_f32_e32 v85, v91, v91
	v_mul_f32_e32 v86, v93, v93
	v_fmac_f32_e32 v85, v90, v90
	v_fmac_f32_e32 v86, v92, v92
	v_add_f32_e32 v85, v85, v86
	v_mul_f32_e32 v86, v101, v101
	v_mul_f32_e32 v87, v89, v89
	v_fmac_f32_e32 v86, v100, v100
	v_fmac_f32_e32 v87, v88, v88
	v_add_f32_e32 v86, v86, v87
	v_add_f32_e32 v85, v85, v86
	v_mul_f32_e32 v86, v78, v78
	v_fmac_f32_e32 v86, v0, v0
	v_mul_f32_e32 v87, v82, v82
	v_add_f32_e32 v0, v0, v78
	v_add_f32_e32 v78, v79, v82
	v_fmac_f32_e32 v87, v79, v79
	v_add_f32_e32 v90, v90, v91
	v_add_f32_e32 v91, v92, v93
	v_add_f32_e32 v0, v0, v78
	v_add_f32_e32 v78, v83, v84
	v_add_f32_e32 v79, v80, v81
	v_add_f32_e32 v90, v90, v91
	v_add_f32_e32 v91, v100, v101
	v_add_f32_e32 v88, v88, v89
	v_add_f32_e32 v78, v78, v79
	v_and_b32_e32 v79, 64, v226
	v_add_f32_e32 v88, v91, v88
	v_add_f32_e32 v0, v0, v78
	v_xor_b32_e32 v78, 16, v226
	v_add_u32_e32 v79, 64, v79
	v_add_f32_e32 v88, v90, v88
	v_cmp_lt_i32_e32 vcc, v78, v79
	v_add_f32_e32 v86, v86, v87
	v_mul_f32_e32 v87, v84, v84
	v_mul_f32_e32 v98, v81, v81
	v_add_f32_e32 v88, 0, v88
	v_cndmask_b32_e32 v78, v226, v78, vcc
	v_fmac_f32_e32 v87, v83, v83
	v_add_f32_e32 v0, v0, v88
	v_lshlrev_b32_e32 v78, 2, v78
	v_fmac_f32_e32 v98, v80, v80
	v_mov_b32_e32 v81, v0
	s_nop 1
	v_permlane16_swap_b32_e32 v81, v0
	v_add_f32_e32 v80, v87, v98
	v_add_f32_e32 v80, v86, v80
	v_add_f32_e32 v80, v85, v80
	v_mov_b32_e32 v82, v80
	s_nop 1
	v_permlane16_swap_b32_e32 v82, v80
	s_waitcnt lgkmcnt(0)
	v_add_f32_e32 v0, v0, v81
	v_xor_b32_e32 v81, 32, v226
	v_cmp_lt_i32_e32 vcc, v81, v79
	v_add_f32_e32 v79, v80, v82
	s_nop 0
	v_cndmask_b32_e32 v78, v226, v81, vcc
	v_lshlrev_b32_e32 v81, 2, v78
	v_mov_b32_e32 v78, v0
	s_nop 1
	v_permlane32_swap_b32_e32 v78, v0
	v_mov_b32_e32 v80, v79
	s_nop 1
	v_permlane32_swap_b32_e32 v80, v79
	s_and_saveexec_b64 s[4:5], s[6:7]
	s_cbranch_execz .LBB0_367
	s_waitcnt lgkmcnt(0)
	v_add_f32_e32 v79, v79, v80
	v_add_f32_e32 v0, v0, v78
	ds_write2st64_b32 v186, v0, v79 offset0:3 offset1:19

; __device__ __forceinline__ unsigned cvt_pk_bf16(float lo, float hi) { unsigned r; asm volatile("v_cvt_pk_bf16_f32 %0, %1, %2" : "=v"(r) : "v"(lo), "v"(hi)); return r; }
; __device__ __forceinline__ f32x2 gelu_pk(f32x2 v) {
;     const f32x2 av = __builtin_elementwise_abs(v), d = av * 0.2316418882f + 1.0f;
;     f32x2 t; t.x = __builtin_amdgcn_rcpf(d.x); t.y = __builtin_amdgcn_rcpf(d.y);
;     f32x2 q = t * 0.5307027145f + (-0.7265760135f); q = q * t + 0.7107068705f; q = q * t + (-0.142248368f); q = q * t + 0.127414796f; q = q * t;
;     const f32x2 s = (v * v) * (-0.72134752044f);
;     f32x2 e; e.x = __builtin_amdgcn_exp2f(s.x); e.y = __builtin_amdgcn_exp2f(s.y);
;     const f32x2 m = v * (q * e), r = v - m;
;     f32x2 o; o.x = v.x < 0.f ? m.x : r.x; o.y = v.y < 0.f ? m.y : r.y; return o;
; }
;     __device__ __forceinline__ void operator()(const f32x4 (&acc)[2][2][4][2], const Unit& u, int wr, int wc, int fr, int fq) const {
;     ...
;             for (int m = 0; m < 4; ++m) { const int row = row0 + ai * HALF + m * 16; const float rs = rsv[ai][m]; bf16_t* rowp = O + (size_t)row * ldc + col0; float s1 = 0.f, s2 = 0.f;
; #pragma unroll
;                 for (int bj = 0; bj < 2; ++bj) { f32x4 v0 = acc[ai][bj][m][0] * rs, v1 = acc[ai][bj][m][1] * rs;
;                     const f32x2 a = gelu_pk((f32x2){v0[0], v0[1]}), b = gelu_pk((f32x2){v0[2], v0[3]}), c = gelu_pk((f32x2){v1[0], v1[1]}), d = gelu_pk((f32x2){v1[2], v1[3]});
;                     s1 += ((a.x + a.y) + (b.x + b.y)) + ((c.x + c.y) + (d.x + d.y));
;                     s2 += ((a.x * a.x + a.y * a.y) + (b.x * b.x + b.y * b.y)) + ((c.x * c.x + c.y * c.y) + (d.x * d.x + d.y * d.y));
;                     u32x4 w; w.x = cvt_pk_bf16(a.x, a.y); w.y = cvt_pk_bf16(b.x, b.y); w.z = cvt_pk_bf16(c.x, c.y); w.w = cvt_pk_bf16(d.x, d.y);
;                     *(u32x4*)(rowp + bj * HALF) = w; }
.LBB0_368:
	v_add_f32_e32 v0, v94, v95
	s_waitcnt lgkmcnt(0)
	v_add_f32_e32 v78, v96, v97
	v_add_f32_e32 v0, v0, v78
	v_fmamk_f32 v0, v0, 0x3a800000, v224
	v_rsq_f32_e32 v0, v0
	s_mov_b32 s4, 0xbf3a00e3
	v_lshlrev_b64 v[78:79], 12, v[168:169]
	v_lshl_add_u64 v[78:79], s[20:21], 0, v[78:79]
	v_pk_mul_f32 v[70:71], v[70:71], v[0:1] op_sel_hi:[1,0]
	v_pk_mul_f32 v[80:81], v[66:67], v[0:1] op_sel_hi:[1,0]
	v_and_b32_e32 v67, 0x7fffffff, v71
	v_and_b32_e32 v66, 0x7fffffff, v70
	v_pk_fma_f32 v[66:67], v[66:67], s[64:65], 1.0 op_sel_hi:[1,0,0]
	v_pk_mul_f32 v[86:87], v[70:71], v[70:71]
	v_rcp_f32_e32 v82, v66
	v_rcp_f32_e32 v83, v67
	v_mov_b64_e32 v[66:67], s[4:5]
	v_pk_mul_f32 v[86:87], v[86:87], s[76:77] op_sel_hi:[1,0]
	s_nop 0
	v_pk_fma_f32 v[84:85], v[82:83], s[66:67], v[66:67] op_sel_hi:[1,0,0]
	v_exp_f32_e32 v86, v86
	v_pk_fma_f32 v[84:85], v[82:83], v[84:85], s[70:71] op_sel_hi:[1,1,0]
	v_exp_f32_e32 v87, v87
	v_pk_fma_f32 v[84:85], v[82:83], v[84:85], s[72:73] op_sel_hi:[1,1,0]
	v_pk_mul_f32 v[72:73], v[72:73], v[0:1] op_sel_hi:[1,0]
	v_pk_fma_f32 v[84:85], v[82:83], v[84:85], s[74:75] op_sel_hi:[1,1,0]
	v_pk_mul_f32 v[68:69], v[68:69], v[0:1] op_sel_hi:[1,0]
	v_pk_mul_f32 v[82:83], v[82:83], v[84:85]
	v_pk_mul_f32 v[84:85], v[72:73], v[72:73]
	v_pk_mul_f32 v[82:83], v[86:87], v[82:83]
	v_pk_mul_f32 v[84:85], v[84:85], s[76:77] op_sel_hi:[1,0]
	v_max_f32_e32 v86, 0, v70
	v_max_f32_e32 v87, 0, v71
	v_fma_f32 v70, -|v70|, v82, v86
	v_fma_f32 v71, -|v71|, v83, v87
	v_exp_f32_e32 v84, v84
	s_nop 0
	s_nop 0
	v_and_b32_e32 v82, 0x7fffffff, v72
	v_exp_f32_e32 v85, v85
	s_nop 0
	v_and_b32_e32 v83, 0x7fffffff, v73
	v_pk_fma_f32 v[82:83], v[82:83], s[64:65], 1.0 op_sel_hi:[1,0,0]
	s_nop 0
	v_rcp_f32_e32 v82, v82
	v_rcp_f32_e32 v83, v83
	v_lshl_add_u64 v[78:79], v[160:161], 1, v[78:79]
	v_pk_mul_f32 v[62:63], v[62:63], v[0:1] op_sel_hi:[1,0]
	v_pk_mul_f32 v[64:65], v[64:65], v[0:1] op_sel_hi:[1,0]
	v_pk_fma_f32 v[86:87], v[82:83], s[66:67], v[66:67] op_sel_hi:[1,0,0]
	v_pk_mul_f32 v[60:61], v[60:61], v[0:1] op_sel_hi:[1,0]
	v_pk_fma_f32 v[86:87], v[82:83], v[86:87], s[70:71] op_sel_hi:[1,1,0]
	s_nop 0
	v_pk_fma_f32 v[86:87], v[82:83], v[86:87], s[72:73] op_sel_hi:[1,1,0]
	s_nop 0
	v_pk_fma_f32 v[86:87], v[82:83], v[86:87], s[74:75] op_sel_hi:[1,1,0]
	s_nop 0
	v_pk_mul_f32 v[82:83], v[82:83], v[86:87]
	v_pk_mul_f32 v[86:87], v[80:81], v[80:81]
	v_pk_mul_f32 v[82:83], v[84:85], v[82:83]
	v_pk_mul_f32 v[86:87], v[86:87], s[76:77] op_sel_hi:[1,0]
	v_max_f32_e32 v84, 0, v72
	v_max_f32_e32 v85, 0, v73
	v_fma_f32 v72, -|v72|, v82, v84
	v_fma_f32 v73, -|v73|, v83, v85
	v_exp_f32_e32 v86, v86
	s_nop 0
	s_nop 0
	v_and_b32_e32 v82, 0x7fffffff, v80
	v_exp_f32_e32 v87, v87
	s_nop 0
	v_and_b32_e32 v83, 0x7fffffff, v81
	v_pk_fma_f32 v[82:83], v[82:83], s[64:65], 1.0 op_sel_hi:[1,0,0]
	s_nop 0
	v_rcp_f32_e32 v82, v82
	v_rcp_f32_e32 v83, v83
	s_nop 0
	v_pk_fma_f32 v[84:85], v[82:83], s[66:67], v[66:67] op_sel_hi:[1,0,0]
	s_nop 0
	v_pk_fma_f32 v[84:85], v[82:83], v[84:85], s[70:71] op_sel_hi:[1,1,0]
	s_nop 0
	v_pk_fma_f32 v[84:85], v[82:83], v[84:85], s[72:73] op_sel_hi:[1,1,0]
	s_nop 0
	v_pk_fma_f32 v[84:85], v[82:83], v[84:85], s[74:75] op_sel_hi:[1,1,0]
	s_nop 0
	v_pk_mul_f32 v[82:83], v[82:83], v[84:85]
	v_pk_mul_f32 v[84:85], v[68:69], v[68:69]
	v_pk_mul_f32 v[82:83], v[86:87], v[82:83]
	v_pk_mul_f32 v[84:85], v[84:85], s[76:77] op_sel_hi:[1,0]
	v_max_f32_e32 v86, 0, v80
	v_max_f32_e32 v87, 0, v81
	v_fma_f32 v80, -|v80|, v82, v86
	v_fma_f32 v81, -|v81|, v83, v87
	v_exp_f32_e32 v84, v84
	s_nop 0
	s_nop 0
	v_and_b32_e32 v82, 0x7fffffff, v68
	v_exp_f32_e32 v85, v85
	s_nop 0
	v_and_b32_e32 v83, 0x7fffffff, v69
	v_pk_fma_f32 v[82:83], v[82:83], s[64:65], 1.0 op_sel_hi:[1,0,0]
	s_nop 0
	v_rcp_f32_e32 v82, v82
	v_rcp_f32_e32 v83, v83
	s_nop 0
	v_pk_fma_f32 v[86:87], v[82:83], s[66:67], v[66:67] op_sel_hi:[1,0,0]
	s_nop 0
	v_pk_fma_f32 v[86:87], v[82:83], v[86:87], s[70:71] op_sel_hi:[1,1,0]
	s_nop 0
	v_pk_fma_f32 v[86:87], v[82:83], v[86:87], s[72:73] op_sel_hi:[1,1,0]
	s_nop 0
	v_pk_fma_f32 v[86:87], v[82:83], v[86:87], s[74:75] op_sel_hi:[1,1,0]
	s_nop 0
	v_pk_mul_f32 v[82:83], v[82:83], v[86:87]
	v_pk_mul_f32 v[86:87], v[62:63], v[62:63]
	v_pk_mul_f32 v[82:83], v[84:85], v[82:83]
	v_pk_mul_f32 v[86:87], v[86:87], s[76:77] op_sel_hi:[1,0]
	v_max_f32_e32 v84, 0, v68
	v_max_f32_e32 v85, 0, v69
	v_fma_f32 v68, -|v68|, v82, v84
	v_fma_f32 v69, -|v69|, v83, v85
	v_exp_f32_e32 v86, v86
	s_nop 0
	s_nop 0
	v_cvt_pk_bf16_f32 v82, v70, v71
	v_exp_f32_e32 v87, v87
	s_nop 0
	s_nop 0
	v_cvt_pk_bf16_f32 v83, v72, v73
	v_cvt_pk_bf16_f32 v84, v80, v81
	v_cvt_pk_bf16_f32 v85, v68, v69
	global_store_dwordx4 v[78:79], v[82:85], off
	s_nop 0
	s_nop 0
	v_pk_mul_f32 v[82:83], v[58:59], v[0:1] op_sel_hi:[1,0]
	v_and_b32_e32 v59, 0x7fffffff, v63
	v_and_b32_e32 v58, 0x7fffffff, v62
	v_pk_fma_f32 v[58:59], v[58:59], s[64:65], 1.0 op_sel_hi:[1,0,0]
	s_nop 0
	v_rcp_f32_e32 v58, v58
	v_rcp_f32_e32 v59, v59
	s_nop 0
	v_pk_fma_f32 v[84:85], v[58:59], s[66:67], v[66:67] op_sel_hi:[1,0,0]
	s_nop 0
	v_pk_fma_f32 v[84:85], v[58:59], v[84:85], s[70:71] op_sel_hi:[1,1,0]
	s_nop 0
	v_pk_fma_f32 v[84:85], v[58:59], v[84:85], s[72:73] op_sel_hi:[1,1,0]
	s_nop 0
	v_pk_fma_f32 v[84:85], v[58:59], v[84:85], s[74:75] op_sel_hi:[1,1,0]
; __device__ __forceinline__ unsigned cvt_pk_bf16(float lo, float hi) { unsigned r; asm volatile("v_cvt_pk_bf16_f32 %0, %1, %2" : "=v"(r) : "v"(lo), "v"(hi)); return r; }
; __device__ __forceinline__ f32x2 gelu_pk(f32x2 v) {
;     const f32x2 av = __builtin_elementwise_abs(v), d = av * 0.2316418882f + 1.0f;
;     f32x2 t; t.x = __builtin_amdgcn_rcpf(d.x); t.y = __builtin_amdgcn_rcpf(d.y);
;     f32x2 q = t * 0.5307027145f + (-0.7265760135f); q = q * t + 0.7107068705f; q = q * t + (-0.142248368f); q = q * t + 0.127414796f; q = q * t;
;     const f32x2 s = (v * v) * (-0.72134752044f);
;     f32x2 e; e.x = __builtin_amdgcn_exp2f(s.x); e.y = __builtin_amdgcn_exp2f(s.y);
;     const f32x2 m = v * (q * e), r = v - m;
;     f32x2 o; o.x = v.x < 0.f ? m.x : r.x; o.y = v.y < 0.f ? m.y : r.y; return o;
; }
;     __device__ __forceinline__ void operator()(const f32x4 (&acc)[2][2][4][2], const Unit& u, int wr, int wc, int fr, int fq) const {
;     ...
;                 for (int bj = 0; bj < 2; ++bj) { f32x4 v0 = acc[ai][bj][m][0] * rs, v1 = acc[ai][bj][m][1] * rs;
;                     const f32x2 a = gelu_pk((f32x2){v0[0], v0[1]}), b = gelu_pk((f32x2){v0[2], v0[3]}), c = gelu_pk((f32x2){v1[0], v1[1]}), d = gelu_pk((f32x2){v1[2], v1[3]});
;                     s1 += ((a.x + a.y) + (b.x + b.y)) + ((c.x + c.y) + (d.x + d.y));
;                     s2 += ((a.x * a.x + a.y * a.y) + (b.x * b.x + b.y * b.y)) + ((c.x * c.x + c.y * c.y) + (d.x * d.x + d.y * d.y));
;                     u32x4 w; w.x = cvt_pk_bf16(a.x, a.y); w.y = cvt_pk_bf16(b.x, b.y); w.z = cvt_pk_bf16(c.x, c.y); w.w = cvt_pk_bf16(d.x, d.y);
;                     *(u32x4*)(rowp + bj * HALF) = w; }
;                 if (isv) { s1 += __shfl_xor(s1, 16); s1 += __shfl_xor(s1, 32); s2 += __shfl_xor(s2, 16); s2 += __shfl_xor(s2, 32);
;                     if (fq == 0) { const int rl = ai * HALF + wr * 64 + m * 16 + fr; part[rl * 4 + wc] = s1; part[1024 + rl * 4 + wc] = s2; } } }
	s_nop 0
	v_pk_mul_f32 v[58:59], v[58:59], v[84:85]
	v_pk_mul_f32 v[84:85], v[64:65], v[64:65]
	v_pk_mul_f32 v[58:59], v[86:87], v[58:59]
	v_pk_mul_f32 v[84:85], v[84:85], s[76:77] op_sel_hi:[1,0]
	v_max_f32_e32 v86, 0, v62
	v_max_f32_e32 v87, 0, v63
	v_fma_f32 v0, -|v62|, v58, v86
	v_fma_f32 v58, -|v63|, v59, v87
	v_and_b32_e32 v62, 0x7fffffff, v64
	s_nop 0
	s_nop 0
	v_and_b32_e32 v63, 0x7fffffff, v65
	v_pk_fma_f32 v[62:63], v[62:63], s[64:65], 1.0 op_sel_hi:[1,0,0]
	s_nop 0
	v_rcp_f32_e32 v62, v62
	v_rcp_f32_e32 v63, v63
	v_exp_f32_e32 v84, v84
	v_exp_f32_e32 v85, v85
	s_nop 0
	v_pk_fma_f32 v[86:87], v[62:63], s[66:67], v[66:67] op_sel_hi:[1,0,0]
	s_nop 0
	v_pk_fma_f32 v[86:87], v[62:63], v[86:87], s[70:71] op_sel_hi:[1,1,0]
	s_nop 0
	v_pk_fma_f32 v[86:87], v[62:63], v[86:87], s[72:73] op_sel_hi:[1,1,0]
	s_nop 0
	v_pk_fma_f32 v[86:87], v[62:63], v[86:87], s[74:75] op_sel_hi:[1,1,0]
	s_nop 0
	v_pk_mul_f32 v[62:63], v[62:63], v[86:87]
	v_pk_mul_f32 v[86:87], v[82:83], v[82:83]
	v_pk_mul_f32 v[62:63], v[84:85], v[62:63]
	v_pk_mul_f32 v[86:87], v[86:87], s[76:77] op_sel_hi:[1,0]
	v_max_f32_e32 v84, 0, v64
	v_max_f32_e32 v85, 0, v65
	v_fma_f32 v59, -|v64|, v62, v84
	v_fma_f32 v62, -|v65|, v63, v85
	v_and_b32_e32 v64, 0x7fffffff, v82
	s_nop 0
	s_nop 0
	v_and_b32_e32 v65, 0x7fffffff, v83
	v_pk_fma_f32 v[64:65], v[64:65], s[64:65], 1.0 op_sel_hi:[1,0,0]
	s_nop 0
	v_rcp_f32_e32 v64, v64
	v_rcp_f32_e32 v65, v65
	v_exp_f32_e32 v86, v86
	v_exp_f32_e32 v87, v87
	s_nop 0
	v_pk_fma_f32 v[84:85], v[64:65], s[66:67], v[66:67] op_sel_hi:[1,0,0]
	s_nop 0
	v_pk_fma_f32 v[84:85], v[64:65], v[84:85], s[70:71] op_sel_hi:[1,1,0]
	s_nop 0
	v_pk_fma_f32 v[84:85], v[64:65], v[84:85], s[72:73] op_sel_hi:[1,1,0]
	s_nop 0
	v_pk_fma_f32 v[84:85], v[64:65], v[84:85], s[74:75] op_sel_hi:[1,1,0]
	s_nop 0
	v_pk_mul_f32 v[64:65], v[64:65], v[84:85]
	v_pk_mul_f32 v[84:85], v[60:61], v[60:61]
	v_pk_mul_f32 v[64:65], v[86:87], v[64:65]
	s_nop 0
	v_max_f32_e32 v86, 0, v82
	v_max_f32_e32 v87, 0, v83
	v_fma_f32 v63, -|v82|, v64, v86
	v_fma_f32 v64, -|v83|, v65, v87
	v_and_b32_e32 v82, 0x7fffffff, v60
	s_nop 0
	s_nop 0
	v_and_b32_e32 v83, 0x7fffffff, v61
	v_pk_fma_f32 v[82:83], v[82:83], s[64:65], 1.0 op_sel_hi:[1,0,0]
	s_nop 0
	v_rcp_f32_e32 v82, v82
	v_rcp_f32_e32 v83, v83
	s_nop 0
	v_pk_fma_f32 v[66:67], v[82:83], s[66:67], v[66:67] op_sel_hi:[1,0,0]
	s_nop 0
	v_pk_fma_f32 v[66:67], v[82:83], v[66:67], s[70:71] op_sel_hi:[1,1,0]
	s_nop 0
	v_pk_fma_f32 v[66:67], v[82:83], v[66:67], s[72:73] op_sel_hi:[1,1,0]
	s_nop 0
	v_pk_fma_f32 v[66:67], v[82:83], v[66:67], s[74:75] op_sel_hi:[1,1,0]
	s_nop 0
	v_pk_mul_f32 v[66:67], v[82:83], v[66:67]
	v_pk_mul_f32 v[82:83], v[84:85], s[76:77] op_sel_hi:[1,0]
	s_nop 0
	v_exp_f32_e32 v82, v82
	v_exp_f32_e32 v83, v83
	s_nop 0
	v_pk_mul_f32 v[66:67], v[82:83], v[66:67]
	s_nop 0
	v_max_f32_e32 v82, 0, v60
	v_max_f32_e32 v83, 0, v61
	v_fma_f32 v60, -|v60|, v66, v82
	v_fma_f32 v61, -|v61|, v67, v83
	s_nop 0
	s_nop 0
	s_nop 0
	v_cvt_pk_bf16_f32 v82, v0, v58
	s_nop 1
	s_nop 0
	s_and_b64 vcc, exec, s[10:11]
	v_cvt_pk_bf16_f32 v83, v59, v62
	v_cvt_pk_bf16_f32 v84, v63, v64
	v_cvt_pk_bf16_f32 v85, v60, v61
	global_store_dwordx4 v[78:79], v[82:85], off offset:256
	s_cbranch_vccnz .LBB0_372
	v_mul_f32_e32 v65, v71, v71
	v_mul_f32_e32 v66, v73, v73
	v_fmac_f32_e32 v65, v70, v70
	v_fmac_f32_e32 v66, v72, v72
	v_add_f32_e32 v65, v65, v66
	v_mul_f32_e32 v66, v81, v81
	v_mul_f32_e32 v67, v69, v69
	v_fmac_f32_e32 v66, v80, v80
	v_fmac_f32_e32 v67, v68, v68
	v_add_f32_e32 v66, v66, v67
	v_add_f32_e32 v65, v65, v66
	v_mul_f32_e32 v66, v58, v58
	v_fmac_f32_e32 v66, v0, v0
	v_mul_f32_e32 v67, v62, v62
	v_add_f32_e32 v0, v0, v58
	v_add_f32_e32 v58, v59, v62
	v_fmac_f32_e32 v67, v59, v59
	v_add_f32_e32 v70, v70, v71
	v_add_f32_e32 v71, v72, v73
	v_add_f32_e32 v0, v0, v58
	v_add_f32_e32 v58, v63, v64
	v_add_f32_e32 v59, v60, v61
	v_add_f32_e32 v70, v70, v71
	v_add_f32_e32 v71, v80, v81
	v_add_f32_e32 v68, v68, v69
	v_add_f32_e32 v58, v58, v59
	v_and_b32_e32 v59, 64, v226
	v_add_f32_e32 v68, v71, v68
	v_add_f32_e32 v0, v0, v58
	v_xor_b32_e32 v58, 16, v226
	v_add_u32_e32 v59, 64, v59
	v_add_f32_e32 v68, v70, v68
	v_cmp_lt_i32_e32 vcc, v58, v59
	v_add_f32_e32 v66, v66, v67
	v_mul_f32_e32 v67, v64, v64
	v_mul_f32_e32 v78, v61, v61
	v_add_f32_e32 v68, 0, v68
	v_cndmask_b32_e32 v58, v226, v58, vcc
	v_fmac_f32_e32 v67, v63, v63
	v_add_f32_e32 v0, v0, v68
	v_lshlrev_b32_e32 v58, 2, v58
	v_fmac_f32_e32 v78, v60, v60
	v_mov_b32_e32 v61, v0
	s_nop 1
	v_permlane16_swap_b32_e32 v61, v0
	v_add_f32_e32 v60, v67, v78
	v_add_f32_e32 v60, v66, v60
	v_add_f32_e32 v60, v65, v60
	v_mov_b32_e32 v62, v60
	s_nop 1
	v_permlane16_swap_b32_e32 v62, v60
	s_waitcnt lgkmcnt(0)
	v_add_f32_e32 v0, v0, v61
	v_xor_b32_e32 v61, 32, v226
	v_cmp_lt_i32_e32 vcc, v61, v59
	v_add_f32_e32 v59, v60, v62
	s_nop 0
	v_cndmask_b32_e32 v58, v226, v61, vcc
	v_lshlrev_b32_e32 v61, 2, v58
	v_mov_b32_e32 v58, v0
	s_nop 1
	v_permlane32_swap_b32_e32 v58, v0
	v_mov_b32_e32 v60, v59
	s_nop 1
	v_permlane32_swap_b32_e32 v60, v59
	s_and_saveexec_b64 s[4:5], s[6:7]
	s_cbranch_execz .LBB0_371
	s_waitcnt lgkmcnt(0)
	v_add_f32_e32 v59, v59, v60
	v_add_f32_e32 v0, v0, v58
	ds_write2st64_b32 v186, v0, v59 offset0:8 offset1:24

; __device__ __forceinline__ unsigned cvt_pk_bf16(float lo, float hi) { unsigned r; asm volatile("v_cvt_pk_bf16_f32 %0, %1, %2" : "=v"(r) : "v"(lo), "v"(hi)); return r; }
; __device__ __forceinline__ f32x2 gelu_pk(f32x2 v) {
;     const f32x2 av = __builtin_elementwise_abs(v), d = av * 0.2316418882f + 1.0f;
;     f32x2 t; t.x = __builtin_amdgcn_rcpf(d.x); t.y = __builtin_amdgcn_rcpf(d.y);
;     f32x2 q = t * 0.5307027145f + (-0.7265760135f); q = q * t + 0.7107068705f; q = q * t + (-0.142248368f); q = q * t + 0.127414796f; q = q * t;
;     const f32x2 s = (v * v) * (-0.72134752044f);
;     f32x2 e; e.x = __builtin_amdgcn_exp2f(s.x); e.y = __builtin_amdgcn_exp2f(s.y);
;     const f32x2 m = v * (q * e), r = v - m;
;     f32x2 o; o.x = v.x < 0.f ? m.x : r.x; o.y = v.y < 0.f ? m.y : r.y; return o;
; }
;     __device__ __forceinline__ void operator()(const f32x4 (&acc)[2][2][4][2], const Unit& u, int wr, int wc, int fr, int fq) const {
;     ...
;             for (int m = 0; m < 4; ++m) { const int row = row0 + ai * HALF + m * 16; const float rs = rsv[ai][m]; bf16_t* rowp = O + (size_t)row * ldc + col0; float s1 = 0.f, s2 = 0.f;
; #pragma unroll
;                 for (int bj = 0; bj < 2; ++bj) { f32x4 v0 = acc[ai][bj][m][0] * rs, v1 = acc[ai][bj][m][1] * rs;
;                     const f32x2 a = gelu_pk((f32x2){v0[0], v0[1]}), b = gelu_pk((f32x2){v0[2], v0[3]}), c = gelu_pk((f32x2){v1[0], v1[1]}), d = gelu_pk((f32x2){v1[2], v1[3]});
;                     s1 += ((a.x + a.y) + (b.x + b.y)) + ((c.x + c.y) + (d.x + d.y));
;                     s2 += ((a.x * a.x + a.y * a.y) + (b.x * b.x + b.y * b.y)) + ((c.x * c.x + c.y * c.y) + (d.x * d.x + d.y * d.y));
;                     u32x4 w; w.x = cvt_pk_bf16(a.x, a.y); w.y = cvt_pk_bf16(b.x, b.y); w.z = cvt_pk_bf16(c.x, c.y); w.w = cvt_pk_bf16(d.x, d.y);
;                     *(u32x4*)(rowp + bj * HALF) = w; }
.LBB0_372:
	v_add_f32_e32 v0, v74, v75
	s_waitcnt lgkmcnt(0)
	v_add_f32_e32 v58, v76, v77
	v_add_f32_e32 v0, v0, v58
	v_fmamk_f32 v0, v0, 0x3a800000, v224
	v_rsq_f32_e32 v0, v0
	s_mov_b32 s4, 0xbf3a00e3
	v_lshlrev_b64 v[58:59], 12, v[166:167]
	v_lshl_add_u64 v[58:59], s[20:21], 0, v[58:59]
	v_pk_mul_f32 v[50:51], v[50:51], v[0:1] op_sel_hi:[1,0]
	v_pk_mul_f32 v[60:61], v[46:47], v[0:1] op_sel_hi:[1,0]
	v_and_b32_e32 v47, 0x7fffffff, v51
	v_and_b32_e32 v46, 0x7fffffff, v50
	v_pk_fma_f32 v[46:47], v[46:47], s[64:65], 1.0 op_sel_hi:[1,0,0]
	v_pk_mul_f32 v[66:67], v[50:51], v[50:51]
	v_rcp_f32_e32 v62, v46
	v_rcp_f32_e32 v63, v47
	v_mov_b64_e32 v[46:47], s[4:5]
	v_pk_mul_f32 v[66:67], v[66:67], s[76:77] op_sel_hi:[1,0]
	s_nop 0
	v_pk_fma_f32 v[64:65], v[62:63], s[66:67], v[46:47] op_sel_hi:[1,0,0]
	v_exp_f32_e32 v66, v66
	v_pk_fma_f32 v[64:65], v[62:63], v[64:65], s[70:71] op_sel_hi:[1,1,0]
	v_exp_f32_e32 v67, v67
	v_pk_fma_f32 v[64:65], v[62:63], v[64:65], s[72:73] op_sel_hi:[1,1,0]
	v_pk_mul_f32 v[52:53], v[52:53], v[0:1] op_sel_hi:[1,0]
	v_pk_fma_f32 v[64:65], v[62:63], v[64:65], s[74:75] op_sel_hi:[1,1,0]
	v_pk_mul_f32 v[48:49], v[48:49], v[0:1] op_sel_hi:[1,0]
	v_pk_mul_f32 v[62:63], v[62:63], v[64:65]
	v_pk_mul_f32 v[64:65], v[52:53], v[52:53]
	v_pk_mul_f32 v[62:63], v[66:67], v[62:63]
	v_pk_mul_f32 v[64:65], v[64:65], s[76:77] op_sel_hi:[1,0]
	v_max_f32_e32 v66, 0, v50
	v_max_f32_e32 v67, 0, v51
	v_fma_f32 v50, -|v50|, v62, v66
	v_fma_f32 v51, -|v51|, v63, v67
	v_exp_f32_e32 v64, v64
	s_nop 0
	s_nop 0
	v_and_b32_e32 v62, 0x7fffffff, v52
	v_exp_f32_e32 v65, v65
	s_nop 0
	v_and_b32_e32 v63, 0x7fffffff, v53
	v_pk_fma_f32 v[62:63], v[62:63], s[64:65], 1.0 op_sel_hi:[1,0,0]
	s_nop 0
	v_rcp_f32_e32 v62, v62
	v_rcp_f32_e32 v63, v63
	v_lshl_add_u64 v[58:59], v[160:161], 1, v[58:59]
	v_pk_mul_f32 v[42:43], v[42:43], v[0:1] op_sel_hi:[1,0]
	v_pk_mul_f32 v[44:45], v[44:45], v[0:1] op_sel_hi:[1,0]
	v_pk_fma_f32 v[66:67], v[62:63], s[66:67], v[46:47] op_sel_hi:[1,0,0]
	v_pk_mul_f32 v[40:41], v[40:41], v[0:1] op_sel_hi:[1,0]
	v_pk_fma_f32 v[66:67], v[62:63], v[66:67], s[70:71] op_sel_hi:[1,1,0]
	s_nop 0
	v_pk_fma_f32 v[66:67], v[62:63], v[66:67], s[72:73] op_sel_hi:[1,1,0]
	s_nop 0
	v_pk_fma_f32 v[66:67], v[62:63], v[66:67], s[74:75] op_sel_hi:[1,1,0]
	s_nop 0
	v_pk_mul_f32 v[62:63], v[62:63], v[66:67]
	v_pk_mul_f32 v[66:67], v[60:61], v[60:61]
	v_pk_mul_f32 v[62:63], v[64:65], v[62:63]
	v_pk_mul_f32 v[66:67], v[66:67], s[76:77] op_sel_hi:[1,0]
	v_max_f32_e32 v64, 0, v52
	v_max_f32_e32 v65, 0, v53
	v_fma_f32 v52, -|v52|, v62, v64
	v_fma_f32 v53, -|v53|, v63, v65
	v_exp_f32_e32 v66, v66
	s_nop 0
	s_nop 0
	v_and_b32_e32 v62, 0x7fffffff, v60
	v_exp_f32_e32 v67, v67
	s_nop 0
	v_and_b32_e32 v63, 0x7fffffff, v61
	v_pk_fma_f32 v[62:63], v[62:63], s[64:65], 1.0 op_sel_hi:[1,0,0]
	s_nop 0
	v_rcp_f32_e32 v62, v62
	v_rcp_f32_e32 v63, v63
	s_nop 0
	v_pk_fma_f32 v[64:65], v[62:63], s[66:67], v[46:47] op_sel_hi:[1,0,0]
	s_nop 0
	v_pk_fma_f32 v[64:65], v[62:63], v[64:65], s[70:71] op_sel_hi:[1,1,0]
	s_nop 0
	v_pk_fma_f32 v[64:65], v[62:63], v[64:65], s[72:73] op_sel_hi:[1,1,0]
	s_nop 0
	v_pk_fma_f32 v[64:65], v[62:63], v[64:65], s[74:75] op_sel_hi:[1,1,0]
	s_nop 0
	v_pk_mul_f32 v[62:63], v[62:63], v[64:65]
	v_pk_mul_f32 v[64:65], v[48:49], v[48:49]
	v_pk_mul_f32 v[62:63], v[66:67], v[62:63]
	v_pk_mul_f32 v[64:65], v[64:65], s[76:77] op_sel_hi:[1,0]
	v_max_f32_e32 v66, 0, v60
	v_max_f32_e32 v67, 0, v61
	v_fma_f32 v60, -|v60|, v62, v66
	v_fma_f32 v61, -|v61|, v63, v67
	v_exp_f32_e32 v64, v64
	s_nop 0
	s_nop 0
	v_and_b32_e32 v62, 0x7fffffff, v48
	v_exp_f32_e32 v65, v65
	s_nop 0
	v_and_b32_e32 v63, 0x7fffffff, v49
	v_pk_fma_f32 v[62:63], v[62:63], s[64:65], 1.0 op_sel_hi:[1,0,0]
	s_nop 0
	v_rcp_f32_e32 v62, v62
	v_rcp_f32_e32 v63, v63
	s_nop 0
	v_pk_fma_f32 v[66:67], v[62:63], s[66:67], v[46:47] op_sel_hi:[1,0,0]
	s_nop 0
	v_pk_fma_f32 v[66:67], v[62:63], v[66:67], s[70:71] op_sel_hi:[1,1,0]
	s_nop 0
	v_pk_fma_f32 v[66:67], v[62:63], v[66:67], s[72:73] op_sel_hi:[1,1,0]
	s_nop 0
	v_pk_fma_f32 v[66:67], v[62:63], v[66:67], s[74:75] op_sel_hi:[1,1,0]
	s_nop 0
	v_pk_mul_f32 v[62:63], v[62:63], v[66:67]
	v_pk_mul_f32 v[66:67], v[42:43], v[42:43]
	v_pk_mul_f32 v[62:63], v[64:65], v[62:63]
	v_pk_mul_f32 v[66:67], v[66:67], s[76:77] op_sel_hi:[1,0]
	v_max_f32_e32 v64, 0, v48
	v_max_f32_e32 v65, 0, v49
	v_fma_f32 v48, -|v48|, v62, v64
	v_fma_f32 v49, -|v49|, v63, v65
	v_exp_f32_e32 v66, v66
	s_nop 0
	s_nop 0
	v_cvt_pk_bf16_f32 v62, v50, v51
	v_exp_f32_e32 v67, v67
	s_nop 0
	s_nop 0
	v_cvt_pk_bf16_f32 v63, v52, v53
	v_cvt_pk_bf16_f32 v64, v60, v61
	v_cvt_pk_bf16_f32 v65, v48, v49
	global_store_dwordx4 v[58:59], v[62:65], off
	s_nop 0
	s_nop 0
	v_pk_mul_f32 v[62:63], v[38:39], v[0:1] op_sel_hi:[1,0]
	v_and_b32_e32 v39, 0x7fffffff, v43
	v_and_b32_e32 v38, 0x7fffffff, v42
	v_pk_fma_f32 v[38:39], v[38:39], s[64:65], 1.0 op_sel_hi:[1,0,0]
	s_nop 0
	v_rcp_f32_e32 v38, v38
	v_rcp_f32_e32 v39, v39
	s_nop 0
	v_pk_fma_f32 v[64:65], v[38:39], s[66:67], v[46:47] op_sel_hi:[1,0,0]
	s_nop 0
	v_pk_fma_f32 v[64:65], v[38:39], v[64:65], s[70:71] op_sel_hi:[1,1,0]
	s_nop 0
	v_pk_fma_f32 v[64:65], v[38:39], v[64:65], s[72:73] op_sel_hi:[1,1,0]
	s_nop 0
	v_pk_fma_f32 v[64:65], v[38:39], v[64:65], s[74:75] op_sel_hi:[1,1,0]
; __device__ __forceinline__ unsigned cvt_pk_bf16(float lo, float hi) { unsigned r; asm volatile("v_cvt_pk_bf16_f32 %0, %1, %2" : "=v"(r) : "v"(lo), "v"(hi)); return r; }
; __device__ __forceinline__ f32x2 gelu_pk(f32x2 v) {
;     const f32x2 av = __builtin_elementwise_abs(v), d = av * 0.2316418882f + 1.0f;
;     f32x2 t; t.x = __builtin_amdgcn_rcpf(d.x); t.y = __builtin_amdgcn_rcpf(d.y);
;     f32x2 q = t * 0.5307027145f + (-0.7265760135f); q = q * t + 0.7107068705f; q = q * t + (-0.142248368f); q = q * t + 0.127414796f; q = q * t;
;     const f32x2 s = (v * v) * (-0.72134752044f);
;     f32x2 e; e.x = __builtin_amdgcn_exp2f(s.x); e.y = __builtin_amdgcn_exp2f(s.y);
;     const f32x2 m = v * (q * e), r = v - m;
;     f32x2 o; o.x = v.x < 0.f ? m.x : r.x; o.y = v.y < 0.f ? m.y : r.y; return o;
; }
;     __device__ __forceinline__ void operator()(const f32x4 (&acc)[2][2][4][2], const Unit& u, int wr, int wc, int fr, int fq) const {
;     ...
;                 for (int bj = 0; bj < 2; ++bj) { f32x4 v0 = acc[ai][bj][m][0] * rs, v1 = acc[ai][bj][m][1] * rs;
;                     const f32x2 a = gelu_pk((f32x2){v0[0], v0[1]}), b = gelu_pk((f32x2){v0[2], v0[3]}), c = gelu_pk((f32x2){v1[0], v1[1]}), d = gelu_pk((f32x2){v1[2], v1[3]});
;                     s1 += ((a.x + a.y) + (b.x + b.y)) + ((c.x + c.y) + (d.x + d.y));
;                     s2 += ((a.x * a.x + a.y * a.y) + (b.x * b.x + b.y * b.y)) + ((c.x * c.x + c.y * c.y) + (d.x * d.x + d.y * d.y));
;                     u32x4 w; w.x = cvt_pk_bf16(a.x, a.y); w.y = cvt_pk_bf16(b.x, b.y); w.z = cvt_pk_bf16(c.x, c.y); w.w = cvt_pk_bf16(d.x, d.y);
;                     *(u32x4*)(rowp + bj * HALF) = w; }
;                 if (isv) { s1 += __shfl_xor(s1, 16); s1 += __shfl_xor(s1, 32); s2 += __shfl_xor(s2, 16); s2 += __shfl_xor(s2, 32);
;                     if (fq == 0) { const int rl = ai * HALF + wr * 64 + m * 16 + fr; part[rl * 4 + wc] = s1; part[1024 + rl * 4 + wc] = s2; } } }
	s_nop 0
	v_pk_mul_f32 v[38:39], v[38:39], v[64:65]
	v_pk_mul_f32 v[64:65], v[44:45], v[44:45]
	v_pk_mul_f32 v[38:39], v[66:67], v[38:39]
	v_pk_mul_f32 v[64:65], v[64:65], s[76:77] op_sel_hi:[1,0]
	v_max_f32_e32 v66, 0, v42
	v_max_f32_e32 v67, 0, v43
	v_fma_f32 v0, -|v42|, v38, v66
	v_fma_f32 v38, -|v43|, v39, v67
	v_and_b32_e32 v42, 0x7fffffff, v44
	s_nop 0
	s_nop 0
	v_and_b32_e32 v43, 0x7fffffff, v45
	v_pk_fma_f32 v[42:43], v[42:43], s[64:65], 1.0 op_sel_hi:[1,0,0]
	s_nop 0
	v_rcp_f32_e32 v42, v42
	v_rcp_f32_e32 v43, v43
	v_exp_f32_e32 v64, v64
	v_exp_f32_e32 v65, v65
	s_nop 0
	v_pk_fma_f32 v[66:67], v[42:43], s[66:67], v[46:47] op_sel_hi:[1,0,0]
	s_nop 0
	v_pk_fma_f32 v[66:67], v[42:43], v[66:67], s[70:71] op_sel_hi:[1,1,0]
	s_nop 0
	v_pk_fma_f32 v[66:67], v[42:43], v[66:67], s[72:73] op_sel_hi:[1,1,0]
	s_nop 0
	v_pk_fma_f32 v[66:67], v[42:43], v[66:67], s[74:75] op_sel_hi:[1,1,0]
	s_nop 0
	v_pk_mul_f32 v[42:43], v[42:43], v[66:67]
	v_pk_mul_f32 v[66:67], v[62:63], v[62:63]
	v_pk_mul_f32 v[42:43], v[64:65], v[42:43]
	v_pk_mul_f32 v[66:67], v[66:67], s[76:77] op_sel_hi:[1,0]
	v_max_f32_e32 v64, 0, v44
	v_max_f32_e32 v65, 0, v45
	v_fma_f32 v39, -|v44|, v42, v64
	v_fma_f32 v42, -|v45|, v43, v65
	v_and_b32_e32 v44, 0x7fffffff, v62
	s_nop 0
	s_nop 0
	v_and_b32_e32 v45, 0x7fffffff, v63
	v_pk_fma_f32 v[44:45], v[44:45], s[64:65], 1.0 op_sel_hi:[1,0,0]
	s_nop 0
	v_rcp_f32_e32 v44, v44
	v_rcp_f32_e32 v45, v45
	v_exp_f32_e32 v66, v66
	v_exp_f32_e32 v67, v67
	s_nop 0
	v_pk_fma_f32 v[64:65], v[44:45], s[66:67], v[46:47] op_sel_hi:[1,0,0]
	s_nop 0
	v_pk_fma_f32 v[64:65], v[44:45], v[64:65], s[70:71] op_sel_hi:[1,1,0]
	s_nop 0
	v_pk_fma_f32 v[64:65], v[44:45], v[64:65], s[72:73] op_sel_hi:[1,1,0]
	s_nop 0
	v_pk_fma_f32 v[64:65], v[44:45], v[64:65], s[74:75] op_sel_hi:[1,1,0]
	s_nop 0
	v_pk_mul_f32 v[44:45], v[44:45], v[64:65]
	v_pk_mul_f32 v[64:65], v[40:41], v[40:41]
	v_pk_mul_f32 v[44:45], v[66:67], v[44:45]
	s_nop 0
	v_max_f32_e32 v66, 0, v62
	v_max_f32_e32 v67, 0, v63
	v_fma_f32 v43, -|v62|, v44, v66
	v_fma_f32 v44, -|v63|, v45, v67
	v_and_b32_e32 v62, 0x7fffffff, v40
	s_nop 0
	s_nop 0
	v_and_b32_e32 v63, 0x7fffffff, v41
	v_pk_fma_f32 v[62:63], v[62:63], s[64:65], 1.0 op_sel_hi:[1,0,0]
	s_nop 0
	v_rcp_f32_e32 v62, v62
	v_rcp_f32_e32 v63, v63
	s_nop 0
	v_pk_fma_f32 v[46:47], v[62:63], s[66:67], v[46:47] op_sel_hi:[1,0,0]
	s_nop 0
	v_pk_fma_f32 v[46:47], v[62:63], v[46:47], s[70:71] op_sel_hi:[1,1,0]
	s_nop 0
	v_pk_fma_f32 v[46:47], v[62:63], v[46:47], s[72:73] op_sel_hi:[1,1,0]
	s_nop 0
	v_pk_fma_f32 v[46:47], v[62:63], v[46:47], s[74:75] op_sel_hi:[1,1,0]
	s_nop 0
	v_pk_mul_f32 v[46:47], v[62:63], v[46:47]
	v_pk_mul_f32 v[62:63], v[64:65], s[76:77] op_sel_hi:[1,0]
	s_nop 0
	v_exp_f32_e32 v62, v62
	v_exp_f32_e32 v63, v63
	s_nop 0
	v_pk_mul_f32 v[46:47], v[62:63], v[46:47]
	s_nop 0
	v_max_f32_e32 v62, 0, v40
	v_max_f32_e32 v63, 0, v41
	v_fma_f32 v40, -|v40|, v46, v62
	v_fma_f32 v41, -|v41|, v47, v63
	s_nop 0
	s_nop 0
	s_nop 0
	v_cvt_pk_bf16_f32 v62, v0, v38
	s_nop 1
	s_nop 0
	s_and_b64 vcc, exec, s[10:11]
	v_cvt_pk_bf16_f32 v63, v39, v42
	v_cvt_pk_bf16_f32 v64, v43, v44
	v_cvt_pk_bf16_f32 v65, v40, v41
	global_store_dwordx4 v[58:59], v[62:65], off offset:256
	s_cbranch_vccnz .LBB0_376
	v_mul_f32_e32 v45, v51, v51
	v_mul_f32_e32 v46, v53, v53
	v_fmac_f32_e32 v45, v50, v50
	v_fmac_f32_e32 v46, v52, v52
	v_add_f32_e32 v45, v45, v46
	v_mul_f32_e32 v46, v61, v61
	v_mul_f32_e32 v47, v49, v49
	v_fmac_f32_e32 v46, v60, v60
	v_fmac_f32_e32 v47, v48, v48
	v_add_f32_e32 v46, v46, v47
	v_add_f32_e32 v45, v45, v46
	v_mul_f32_e32 v46, v38, v38
	v_fmac_f32_e32 v46, v0, v0
	v_mul_f32_e32 v47, v42, v42
	v_add_f32_e32 v0, v0, v38
	v_add_f32_e32 v38, v39, v42
	v_fmac_f32_e32 v47, v39, v39
	v_add_f32_e32 v50, v50, v51
	v_add_f32_e32 v51, v52, v53
	v_add_f32_e32 v0, v0, v38
	v_add_f32_e32 v38, v43, v44
	v_add_f32_e32 v39, v40, v41
	v_add_f32_e32 v50, v50, v51
	v_add_f32_e32 v51, v60, v61
	v_add_f32_e32 v48, v48, v49
	v_add_f32_e32 v38, v38, v39
	v_and_b32_e32 v39, 64, v226
	v_add_f32_e32 v48, v51, v48
	v_add_f32_e32 v0, v0, v38
	v_xor_b32_e32 v38, 16, v226
	v_add_u32_e32 v39, 64, v39
	v_add_f32_e32 v48, v50, v48
	v_cmp_lt_i32_e32 vcc, v38, v39
	v_add_f32_e32 v46, v46, v47
	v_mul_f32_e32 v47, v44, v44
	v_mul_f32_e32 v58, v41, v41
	v_add_f32_e32 v48, 0, v48
	v_cndmask_b32_e32 v38, v226, v38, vcc
	v_fmac_f32_e32 v47, v43, v43
	v_add_f32_e32 v0, v0, v48
	v_lshlrev_b32_e32 v38, 2, v38
	v_fmac_f32_e32 v58, v40, v40
	v_mov_b32_e32 v41, v0
	s_nop 1
	v_permlane16_swap_b32_e32 v41, v0
	v_add_f32_e32 v40, v47, v58
	v_add_f32_e32 v40, v46, v40
	v_add_f32_e32 v40, v45, v40
	v_mov_b32_e32 v42, v40
	s_nop 1
	v_permlane16_swap_b32_e32 v42, v40
	s_waitcnt lgkmcnt(0)
	v_add_f32_e32 v0, v0, v41
	v_xor_b32_e32 v41, 32, v226
	v_cmp_lt_i32_e32 vcc, v41, v39
	v_add_f32_e32 v39, v40, v42
	s_nop 0
	v_cndmask_b32_e32 v38, v226, v41, vcc
	v_lshlrev_b32_e32 v41, 2, v38
	v_mov_b32_e32 v38, v0
	s_nop 1
	v_permlane32_swap_b32_e32 v38, v0
	v_mov_b32_e32 v40, v39
	s_nop 1
	v_permlane32_swap_b32_e32 v40, v39
	s_and_saveexec_b64 s[4:5], s[6:7]
	s_cbranch_execz .LBB0_375
	s_waitcnt lgkmcnt(0)
	v_add_f32_e32 v39, v39, v40
	v_add_f32_e32 v0, v0, v38
	ds_write2st64_b32 v186, v0, v39 offset0:9 offset1:25

; __device__ __forceinline__ unsigned cvt_pk_bf16(float lo, float hi) { unsigned r; asm volatile("v_cvt_pk_bf16_f32 %0, %1, %2" : "=v"(r) : "v"(lo), "v"(hi)); return r; }
; __device__ __forceinline__ f32x2 gelu_pk(f32x2 v) {
;     const f32x2 av = __builtin_elementwise_abs(v), d = av * 0.2316418882f + 1.0f;
;     f32x2 t; t.x = __builtin_amdgcn_rcpf(d.x); t.y = __builtin_amdgcn_rcpf(d.y);
;     f32x2 q = t * 0.5307027145f + (-0.7265760135f); q = q * t + 0.7107068705f; q = q * t + (-0.142248368f); q = q * t + 0.127414796f; q = q * t;
;     const f32x2 s = (v * v) * (-0.72134752044f);
;     f32x2 e; e.x = __builtin_amdgcn_exp2f(s.x); e.y = __builtin_amdgcn_exp2f(s.y);
;     const f32x2 m = v * (q * e), r = v - m;
;     f32x2 o; o.x = v.x < 0.f ? m.x : r.x; o.y = v.y < 0.f ? m.y : r.y; return o;
; }
;     __device__ __forceinline__ void operator()(const f32x4 (&acc)[2][2][4][2], const Unit& u, int wr, int wc, int fr, int fq) const {
;     ...
;             for (int m = 0; m < 4; ++m) { const int row = row0 + ai * HALF + m * 16; const float rs = rsv[ai][m]; bf16_t* rowp = O + (size_t)row * ldc + col0; float s1 = 0.f, s2 = 0.f;
; #pragma unroll
;                 for (int bj = 0; bj < 2; ++bj) { f32x4 v0 = acc[ai][bj][m][0] * rs, v1 = acc[ai][bj][m][1] * rs;
;                     const f32x2 a = gelu_pk((f32x2){v0[0], v0[1]}), b = gelu_pk((f32x2){v0[2], v0[3]}), c = gelu_pk((f32x2){v1[0], v1[1]}), d = gelu_pk((f32x2){v1[2], v1[3]});
;                     s1 += ((a.x + a.y) + (b.x + b.y)) + ((c.x + c.y) + (d.x + d.y));
;                     s2 += ((a.x * a.x + a.y * a.y) + (b.x * b.x + b.y * b.y)) + ((c.x * c.x + c.y * c.y) + (d.x * d.x + d.y * d.y));
;                     u32x4 w; w.x = cvt_pk_bf16(a.x, a.y); w.y = cvt_pk_bf16(b.x, b.y); w.z = cvt_pk_bf16(c.x, c.y); w.w = cvt_pk_bf16(d.x, d.y);
;                     *(u32x4*)(rowp + bj * HALF) = w; }
.LBB0_376:
	v_add_f32_e32 v0, v54, v55
	s_waitcnt lgkmcnt(0)
	v_add_f32_e32 v38, v56, v57
	v_add_f32_e32 v0, v0, v38
	v_fmamk_f32 v0, v0, 0x3a800000, v224
	v_rsq_f32_e32 v0, v0
	s_mov_b32 s4, 0xbf3a00e3
	v_lshlrev_b64 v[38:39], 12, v[164:165]
	v_lshl_add_u64 v[38:39], s[20:21], 0, v[38:39]
	v_pk_mul_f32 v[30:31], v[30:31], v[0:1] op_sel_hi:[1,0]
	v_pk_mul_f32 v[40:41], v[26:27], v[0:1] op_sel_hi:[1,0]
	v_and_b32_e32 v27, 0x7fffffff, v31
	v_and_b32_e32 v26, 0x7fffffff, v30
	v_pk_fma_f32 v[26:27], v[26:27], s[64:65], 1.0 op_sel_hi:[1,0,0]
	v_pk_mul_f32 v[46:47], v[30:31], v[30:31]
	v_rcp_f32_e32 v42, v26
	v_rcp_f32_e32 v43, v27
	v_mov_b64_e32 v[26:27], s[4:5]
	v_pk_mul_f32 v[46:47], v[46:47], s[76:77] op_sel_hi:[1,0]
	s_nop 0
	v_pk_fma_f32 v[44:45], v[42:43], s[66:67], v[26:27] op_sel_hi:[1,0,0]
	v_exp_f32_e32 v46, v46
	v_pk_fma_f32 v[44:45], v[42:43], v[44:45], s[70:71] op_sel_hi:[1,1,0]
	v_exp_f32_e32 v47, v47
	v_pk_fma_f32 v[44:45], v[42:43], v[44:45], s[72:73] op_sel_hi:[1,1,0]
	v_pk_mul_f32 v[32:33], v[32:33], v[0:1] op_sel_hi:[1,0]
	v_pk_fma_f32 v[44:45], v[42:43], v[44:45], s[74:75] op_sel_hi:[1,1,0]
	v_pk_mul_f32 v[28:29], v[28:29], v[0:1] op_sel_hi:[1,0]
	v_pk_mul_f32 v[42:43], v[42:43], v[44:45]
	v_pk_mul_f32 v[44:45], v[32:33], v[32:33]
	v_pk_mul_f32 v[42:43], v[46:47], v[42:43]
	v_pk_mul_f32 v[44:45], v[44:45], s[76:77] op_sel_hi:[1,0]
	v_max_f32_e32 v46, 0, v30
	v_max_f32_e32 v47, 0, v31
	v_fma_f32 v30, -|v30|, v42, v46
	v_fma_f32 v31, -|v31|, v43, v47
	v_exp_f32_e32 v44, v44
	s_nop 0
	s_nop 0
	v_and_b32_e32 v42, 0x7fffffff, v32
	v_exp_f32_e32 v45, v45
	s_nop 0
	v_and_b32_e32 v43, 0x7fffffff, v33
	v_pk_fma_f32 v[42:43], v[42:43], s[64:65], 1.0 op_sel_hi:[1,0,0]
	s_nop 0
	v_rcp_f32_e32 v42, v42
	v_rcp_f32_e32 v43, v43
	v_lshl_add_u64 v[38:39], v[160:161], 1, v[38:39]
	v_pk_mul_f32 v[22:23], v[22:23], v[0:1] op_sel_hi:[1,0]
	v_pk_mul_f32 v[24:25], v[24:25], v[0:1] op_sel_hi:[1,0]
	v_pk_fma_f32 v[46:47], v[42:43], s[66:67], v[26:27] op_sel_hi:[1,0,0]
	v_pk_mul_f32 v[20:21], v[20:21], v[0:1] op_sel_hi:[1,0]
	v_pk_fma_f32 v[46:47], v[42:43], v[46:47], s[70:71] op_sel_hi:[1,1,0]
	s_nop 0
	v_pk_fma_f32 v[46:47], v[42:43], v[46:47], s[72:73] op_sel_hi:[1,1,0]
	s_nop 0
	v_pk_fma_f32 v[46:47], v[42:43], v[46:47], s[74:75] op_sel_hi:[1,1,0]
	s_nop 0
	v_pk_mul_f32 v[42:43], v[42:43], v[46:47]
	v_pk_mul_f32 v[46:47], v[40:41], v[40:41]
	v_pk_mul_f32 v[42:43], v[44:45], v[42:43]
	v_pk_mul_f32 v[46:47], v[46:47], s[76:77] op_sel_hi:[1,0]
	v_max_f32_e32 v44, 0, v32
	v_max_f32_e32 v45, 0, v33
	v_fma_f32 v32, -|v32|, v42, v44
	v_fma_f32 v33, -|v33|, v43, v45
	v_exp_f32_e32 v46, v46
	s_nop 0
	s_nop 0
	v_and_b32_e32 v42, 0x7fffffff, v40
	v_exp_f32_e32 v47, v47
	s_nop 0
	v_and_b32_e32 v43, 0x7fffffff, v41
	v_pk_fma_f32 v[42:43], v[42:43], s[64:65], 1.0 op_sel_hi:[1,0,0]
	s_nop 0
	v_rcp_f32_e32 v42, v42
	v_rcp_f32_e32 v43, v43
	s_nop 0
	v_pk_fma_f32 v[44:45], v[42:43], s[66:67], v[26:27] op_sel_hi:[1,0,0]
	s_nop 0
	v_pk_fma_f32 v[44:45], v[42:43], v[44:45], s[70:71] op_sel_hi:[1,1,0]
	s_nop 0
	v_pk_fma_f32 v[44:45], v[42:43], v[44:45], s[72:73] op_sel_hi:[1,1,0]
	s_nop 0
	v_pk_fma_f32 v[44:45], v[42:43], v[44:45], s[74:75] op_sel_hi:[1,1,0]
	s_nop 0
	v_pk_mul_f32 v[42:43], v[42:43], v[44:45]
	v_pk_mul_f32 v[44:45], v[28:29], v[28:29]
	v_pk_mul_f32 v[42:43], v[46:47], v[42:43]
	v_pk_mul_f32 v[44:45], v[44:45], s[76:77] op_sel_hi:[1,0]
	v_max_f32_e32 v46, 0, v40
	v_max_f32_e32 v47, 0, v41
	v_fma_f32 v40, -|v40|, v42, v46
	v_fma_f32 v41, -|v41|, v43, v47
	v_exp_f32_e32 v44, v44
	s_nop 0
	s_nop 0
	v_and_b32_e32 v42, 0x7fffffff, v28
	v_exp_f32_e32 v45, v45
	s_nop 0
	v_and_b32_e32 v43, 0x7fffffff, v29
	v_pk_fma_f32 v[42:43], v[42:43], s[64:65], 1.0 op_sel_hi:[1,0,0]
	s_nop 0
	v_rcp_f32_e32 v42, v42
	v_rcp_f32_e32 v43, v43
	s_nop 0
	v_pk_fma_f32 v[46:47], v[42:43], s[66:67], v[26:27] op_sel_hi:[1,0,0]
	s_nop 0
	v_pk_fma_f32 v[46:47], v[42:43], v[46:47], s[70:71] op_sel_hi:[1,1,0]
	s_nop 0
	v_pk_fma_f32 v[46:47], v[42:43], v[46:47], s[72:73] op_sel_hi:[1,1,0]
	s_nop 0
	v_pk_fma_f32 v[46:47], v[42:43], v[46:47], s[74:75] op_sel_hi:[1,1,0]
	s_nop 0
	v_pk_mul_f32 v[42:43], v[42:43], v[46:47]
	v_pk_mul_f32 v[46:47], v[22:23], v[22:23]
	v_pk_mul_f32 v[42:43], v[44:45], v[42:43]
	v_pk_mul_f32 v[46:47], v[46:47], s[76:77] op_sel_hi:[1,0]
	v_max_f32_e32 v44, 0, v28
	v_max_f32_e32 v45, 0, v29
	v_fma_f32 v28, -|v28|, v42, v44
	v_fma_f32 v29, -|v29|, v43, v45
	v_exp_f32_e32 v46, v46
	s_nop 0
	s_nop 0
	v_cvt_pk_bf16_f32 v42, v30, v31
	v_exp_f32_e32 v47, v47
	s_nop 0
	s_nop 0
	v_cvt_pk_bf16_f32 v43, v32, v33
	v_cvt_pk_bf16_f32 v44, v40, v41
	v_cvt_pk_bf16_f32 v45, v28, v29
	global_store_dwordx4 v[38:39], v[42:45], off
	s_nop 0
	s_nop 0
	v_pk_mul_f32 v[42:43], v[18:19], v[0:1] op_sel_hi:[1,0]
	v_and_b32_e32 v19, 0x7fffffff, v23
	v_and_b32_e32 v18, 0x7fffffff, v22
	v_pk_fma_f32 v[18:19], v[18:19], s[64:65], 1.0 op_sel_hi:[1,0,0]
	s_nop 0
	v_rcp_f32_e32 v18, v18
	v_rcp_f32_e32 v19, v19
	s_nop 0
	v_pk_fma_f32 v[44:45], v[18:19], s[66:67], v[26:27] op_sel_hi:[1,0,0]
	s_nop 0
	v_pk_fma_f32 v[44:45], v[18:19], v[44:45], s[70:71] op_sel_hi:[1,1,0]
	s_nop 0
	v_pk_fma_f32 v[44:45], v[18:19], v[44:45], s[72:73] op_sel_hi:[1,1,0]
	s_nop 0
	v_pk_fma_f32 v[44:45], v[18:19], v[44:45], s[74:75] op_sel_hi:[1,1,0]
; __device__ __forceinline__ unsigned cvt_pk_bf16(float lo, float hi) { unsigned r; asm volatile("v_cvt_pk_bf16_f32 %0, %1, %2" : "=v"(r) : "v"(lo), "v"(hi)); return r; }
; __device__ __forceinline__ f32x2 gelu_pk(f32x2 v) {
;     const f32x2 av = __builtin_elementwise_abs(v), d = av * 0.2316418882f + 1.0f;
;     f32x2 t; t.x = __builtin_amdgcn_rcpf(d.x); t.y = __builtin_amdgcn_rcpf(d.y);
;     f32x2 q = t * 0.5307027145f + (-0.7265760135f); q = q * t + 0.7107068705f; q = q * t + (-0.142248368f); q = q * t + 0.127414796f; q = q * t;
;     const f32x2 s = (v * v) * (-0.72134752044f);
;     f32x2 e; e.x = __builtin_amdgcn_exp2f(s.x); e.y = __builtin_amdgcn_exp2f(s.y);
;     const f32x2 m = v * (q * e), r = v - m;
;     f32x2 o; o.x = v.x < 0.f ? m.x : r.x; o.y = v.y < 0.f ? m.y : r.y; return o;
; }
;     __device__ __forceinline__ void operator()(const f32x4 (&acc)[2][2][4][2], const Unit& u, int wr, int wc, int fr, int fq) const {
;     ...
;                 for (int bj = 0; bj < 2; ++bj) { f32x4 v0 = acc[ai][bj][m][0] * rs, v1 = acc[ai][bj][m][1] * rs;
;                     const f32x2 a = gelu_pk((f32x2){v0[0], v0[1]}), b = gelu_pk((f32x2){v0[2], v0[3]}), c = gelu_pk((f32x2){v1[0], v1[1]}), d = gelu_pk((f32x2){v1[2], v1[3]});
;                     s1 += ((a.x + a.y) + (b.x + b.y)) + ((c.x + c.y) + (d.x + d.y));
;                     s2 += ((a.x * a.x + a.y * a.y) + (b.x * b.x + b.y * b.y)) + ((c.x * c.x + c.y * c.y) + (d.x * d.x + d.y * d.y));
;                     u32x4 w; w.x = cvt_pk_bf16(a.x, a.y); w.y = cvt_pk_bf16(b.x, b.y); w.z = cvt_pk_bf16(c.x, c.y); w.w = cvt_pk_bf16(d.x, d.y);
;                     *(u32x4*)(rowp + bj * HALF) = w; }
;                 if (isv) { s1 += __shfl_xor(s1, 16); s1 += __shfl_xor(s1, 32); s2 += __shfl_xor(s2, 16); s2 += __shfl_xor(s2, 32);
;                     if (fq == 0) { const int rl = ai * HALF + wr * 64 + m * 16 + fr; part[rl * 4 + wc] = s1; part[1024 + rl * 4 + wc] = s2; } } }
	s_nop 0
	v_pk_mul_f32 v[18:19], v[18:19], v[44:45]
	v_pk_mul_f32 v[44:45], v[24:25], v[24:25]
	v_pk_mul_f32 v[18:19], v[46:47], v[18:19]
	v_pk_mul_f32 v[44:45], v[44:45], s[76:77] op_sel_hi:[1,0]
	v_max_f32_e32 v46, 0, v22
	v_max_f32_e32 v47, 0, v23
	v_fma_f32 v0, -|v22|, v18, v46
	v_fma_f32 v18, -|v23|, v19, v47
	v_and_b32_e32 v22, 0x7fffffff, v24
	s_nop 0
	s_nop 0
	v_and_b32_e32 v23, 0x7fffffff, v25
	v_pk_fma_f32 v[22:23], v[22:23], s[64:65], 1.0 op_sel_hi:[1,0,0]
	s_nop 0
	v_rcp_f32_e32 v22, v22
	v_rcp_f32_e32 v23, v23
	v_exp_f32_e32 v44, v44
	v_exp_f32_e32 v45, v45
	s_nop 0
	v_pk_fma_f32 v[46:47], v[22:23], s[66:67], v[26:27] op_sel_hi:[1,0,0]
	s_nop 0
	v_pk_fma_f32 v[46:47], v[22:23], v[46:47], s[70:71] op_sel_hi:[1,1,0]
	s_nop 0
	v_pk_fma_f32 v[46:47], v[22:23], v[46:47], s[72:73] op_sel_hi:[1,1,0]
	s_nop 0
	v_pk_fma_f32 v[46:47], v[22:23], v[46:47], s[74:75] op_sel_hi:[1,1,0]
	s_nop 0
	v_pk_mul_f32 v[22:23], v[22:23], v[46:47]
	v_pk_mul_f32 v[46:47], v[42:43], v[42:43]
	v_pk_mul_f32 v[22:23], v[44:45], v[22:23]
	v_pk_mul_f32 v[46:47], v[46:47], s[76:77] op_sel_hi:[1,0]
	v_max_f32_e32 v44, 0, v24
	v_max_f32_e32 v45, 0, v25
	v_fma_f32 v19, -|v24|, v22, v44
	v_fma_f32 v22, -|v25|, v23, v45
	v_and_b32_e32 v24, 0x7fffffff, v42
	s_nop 0
	s_nop 0
	v_and_b32_e32 v25, 0x7fffffff, v43
	v_pk_fma_f32 v[24:25], v[24:25], s[64:65], 1.0 op_sel_hi:[1,0,0]
	s_nop 0
	v_rcp_f32_e32 v24, v24
	v_rcp_f32_e32 v25, v25
	v_exp_f32_e32 v46, v46
	v_exp_f32_e32 v47, v47
	s_nop 0
	v_pk_fma_f32 v[44:45], v[24:25], s[66:67], v[26:27] op_sel_hi:[1,0,0]
	s_nop 0
	v_pk_fma_f32 v[44:45], v[24:25], v[44:45], s[70:71] op_sel_hi:[1,1,0]
	s_nop 0
	v_pk_fma_f32 v[44:45], v[24:25], v[44:45], s[72:73] op_sel_hi:[1,1,0]
	s_nop 0
	v_pk_fma_f32 v[44:45], v[24:25], v[44:45], s[74:75] op_sel_hi:[1,1,0]
	s_nop 0
	v_pk_mul_f32 v[24:25], v[24:25], v[44:45]
	v_pk_mul_f32 v[44:45], v[20:21], v[20:21]
	v_pk_mul_f32 v[24:25], v[46:47], v[24:25]
	s_nop 0
	v_max_f32_e32 v46, 0, v42
	v_max_f32_e32 v47, 0, v43
	v_fma_f32 v23, -|v42|, v24, v46
	v_fma_f32 v24, -|v43|, v25, v47
	v_and_b32_e32 v42, 0x7fffffff, v20
	s_nop 0
	s_nop 0
	v_and_b32_e32 v43, 0x7fffffff, v21
	v_pk_fma_f32 v[42:43], v[42:43], s[64:65], 1.0 op_sel_hi:[1,0,0]
	s_nop 0
	v_rcp_f32_e32 v42, v42
	v_rcp_f32_e32 v43, v43
	s_nop 0
	v_pk_fma_f32 v[26:27], v[42:43], s[66:67], v[26:27] op_sel_hi:[1,0,0]
	s_nop 0
	v_pk_fma_f32 v[26:27], v[42:43], v[26:27], s[70:71] op_sel_hi:[1,1,0]
	s_nop 0
	v_pk_fma_f32 v[26:27], v[42:43], v[26:27], s[72:73] op_sel_hi:[1,1,0]
	s_nop 0
	v_pk_fma_f32 v[26:27], v[42:43], v[26:27], s[74:75] op_sel_hi:[1,1,0]
	s_nop 0
	v_pk_mul_f32 v[26:27], v[42:43], v[26:27]
	v_pk_mul_f32 v[42:43], v[44:45], s[76:77] op_sel_hi:[1,0]
	s_nop 0
	v_exp_f32_e32 v42, v42
	v_exp_f32_e32 v43, v43
	s_nop 0
	v_pk_mul_f32 v[26:27], v[42:43], v[26:27]
	s_nop 0
	v_max_f32_e32 v42, 0, v20
	v_max_f32_e32 v43, 0, v21
	v_fma_f32 v20, -|v20|, v26, v42
	v_fma_f32 v21, -|v21|, v27, v43
	s_nop 0
	s_nop 0
	s_nop 0
	v_cvt_pk_bf16_f32 v42, v0, v18
	s_nop 1
	s_nop 0
	s_and_b64 vcc, exec, s[10:11]
	v_cvt_pk_bf16_f32 v43, v19, v22
	v_cvt_pk_bf16_f32 v44, v23, v24
	v_cvt_pk_bf16_f32 v45, v20, v21
	global_store_dwordx4 v[38:39], v[42:45], off offset:256
	s_cbranch_vccnz .LBB0_380
	v_mul_f32_e32 v25, v31, v31
	v_mul_f32_e32 v26, v33, v33
	v_fmac_f32_e32 v25, v30, v30
	v_fmac_f32_e32 v26, v32, v32
	v_add_f32_e32 v25, v25, v26
	v_mul_f32_e32 v26, v41, v41
	v_mul_f32_e32 v27, v29, v29
	v_fmac_f32_e32 v26, v40, v40
	v_fmac_f32_e32 v27, v28, v28
	v_add_f32_e32 v26, v26, v27
	v_add_f32_e32 v25, v25, v26
	v_mul_f32_e32 v26, v18, v18
	v_fmac_f32_e32 v26, v0, v0
	v_mul_f32_e32 v27, v22, v22
	v_add_f32_e32 v0, v0, v18
	v_add_f32_e32 v18, v19, v22
	v_fmac_f32_e32 v27, v19, v19
	v_add_f32_e32 v30, v30, v31
	v_add_f32_e32 v31, v32, v33
	v_add_f32_e32 v0, v0, v18
	v_add_f32_e32 v18, v23, v24
	v_add_f32_e32 v19, v20, v21
	v_add_f32_e32 v30, v30, v31
	v_add_f32_e32 v31, v40, v41
	v_add_f32_e32 v28, v28, v29
	v_add_f32_e32 v18, v18, v19
	v_and_b32_e32 v19, 64, v226
	v_add_f32_e32 v28, v31, v28
	v_add_f32_e32 v0, v0, v18
	v_xor_b32_e32 v18, 16, v226
	v_add_u32_e32 v19, 64, v19
	v_add_f32_e32 v28, v30, v28
	v_cmp_lt_i32_e32 vcc, v18, v19
	v_add_f32_e32 v26, v26, v27
	v_mul_f32_e32 v27, v24, v24
	v_mul_f32_e32 v38, v21, v21
	v_add_f32_e32 v28, 0, v28
	v_cndmask_b32_e32 v18, v226, v18, vcc
	v_fmac_f32_e32 v27, v23, v23
	v_add_f32_e32 v0, v0, v28
	v_lshlrev_b32_e32 v18, 2, v18
	v_fmac_f32_e32 v38, v20, v20
	v_mov_b32_e32 v21, v0
	s_nop 1
	v_permlane16_swap_b32_e32 v21, v0
	v_add_f32_e32 v20, v27, v38
	v_add_f32_e32 v20, v26, v20
	v_add_f32_e32 v20, v25, v20
	v_mov_b32_e32 v22, v20
	s_nop 1
	v_permlane16_swap_b32_e32 v22, v20
	s_waitcnt lgkmcnt(0)
	v_add_f32_e32 v0, v0, v21
	v_xor_b32_e32 v21, 32, v226
	v_cmp_lt_i32_e32 vcc, v21, v19
	v_add_f32_e32 v19, v20, v22
	s_nop 0
	v_cndmask_b32_e32 v18, v226, v21, vcc
	v_lshlrev_b32_e32 v21, 2, v18
	v_mov_b32_e32 v18, v0
	s_nop 1
	v_permlane32_swap_b32_e32 v18, v0
	v_mov_b32_e32 v20, v19
	s_nop 1
	v_permlane32_swap_b32_e32 v20, v19
	s_and_saveexec_b64 s[4:5], s[6:7]
	s_cbranch_execz .LBB0_379
	s_waitcnt lgkmcnt(0)
	v_add_f32_e32 v19, v19, v20
	v_add_f32_e32 v0, v0, v18
	ds_write2st64_b32 v186, v0, v19 offset0:10 offset1:26

; __device__ __forceinline__ unsigned cvt_pk_bf16(float lo, float hi) { unsigned r; asm volatile("v_cvt_pk_bf16_f32 %0, %1, %2" : "=v"(r) : "v"(lo), "v"(hi)); return r; }
; __device__ __forceinline__ f32x2 gelu_pk(f32x2 v) {
;     const f32x2 av = __builtin_elementwise_abs(v), d = av * 0.2316418882f + 1.0f;
;     f32x2 t; t.x = __builtin_amdgcn_rcpf(d.x); t.y = __builtin_amdgcn_rcpf(d.y);
;     f32x2 q = t * 0.5307027145f + (-0.7265760135f); q = q * t + 0.7107068705f; q = q * t + (-0.142248368f); q = q * t + 0.127414796f; q = q * t;
;     const f32x2 s = (v * v) * (-0.72134752044f);
;     f32x2 e; e.x = __builtin_amdgcn_exp2f(s.x); e.y = __builtin_amdgcn_exp2f(s.y);
;     const f32x2 m = v * (q * e), r = v - m;
;     f32x2 o; o.x = v.x < 0.f ? m.x : r.x; o.y = v.y < 0.f ? m.y : r.y; return o;
; }
;     __device__ __forceinline__ void operator()(const f32x4 (&acc)[2][2][4][2], const Unit& u, int wr, int wc, int fr, int fq) const {
;     ...
;             for (int m = 0; m < 4; ++m) { const int row = row0 + ai * HALF + m * 16; const float rs = rsv[ai][m]; bf16_t* rowp = O + (size_t)row * ldc + col0; float s1 = 0.f, s2 = 0.f;
; #pragma unroll
;                 for (int bj = 0; bj < 2; ++bj) { f32x4 v0 = acc[ai][bj][m][0] * rs, v1 = acc[ai][bj][m][1] * rs;
;                     const f32x2 a = gelu_pk((f32x2){v0[0], v0[1]}), b = gelu_pk((f32x2){v0[2], v0[3]}), c = gelu_pk((f32x2){v1[0], v1[1]}), d = gelu_pk((f32x2){v1[2], v1[3]});
;                     s1 += ((a.x + a.y) + (b.x + b.y)) + ((c.x + c.y) + (d.x + d.y));
;                     s2 += ((a.x * a.x + a.y * a.y) + (b.x * b.x + b.y * b.y)) + ((c.x * c.x + c.y * c.y) + (d.x * d.x + d.y * d.y));
;                     u32x4 w; w.x = cvt_pk_bf16(a.x, a.y); w.y = cvt_pk_bf16(b.x, b.y); w.z = cvt_pk_bf16(c.x, c.y); w.w = cvt_pk_bf16(d.x, d.y);
;                     *(u32x4*)(rowp + bj * HALF) = w; }
.LBB0_380:
	v_add_f32_e32 v0, v34, v35
	s_waitcnt lgkmcnt(0)
	v_add_f32_e32 v18, v36, v37
	v_add_f32_e32 v0, v0, v18
	v_fmamk_f32 v0, v0, 0x3a800000, v224
	v_rsq_f32_e32 v0, v0
	s_mov_b32 s4, 0xbf3a00e3
	v_lshlrev_b64 v[18:19], 12, v[162:163]
	v_lshl_add_u64 v[18:19], s[20:21], 0, v[18:19]
	v_pk_mul_f32 v[14:15], v[14:15], v[0:1] op_sel_hi:[1,0]
	v_pk_mul_f32 v[20:21], v[10:11], v[0:1] op_sel_hi:[1,0]
	v_and_b32_e32 v11, 0x7fffffff, v15
	v_and_b32_e32 v10, 0x7fffffff, v14
	v_pk_fma_f32 v[10:11], v[10:11], s[64:65], 1.0 op_sel_hi:[1,0,0]
	v_pk_mul_f32 v[26:27], v[14:15], v[14:15]
	v_rcp_f32_e32 v22, v10
	v_rcp_f32_e32 v23, v11
	v_mov_b64_e32 v[10:11], s[4:5]
	v_pk_mul_f32 v[26:27], v[26:27], s[76:77] op_sel_hi:[1,0]
	s_nop 0
	v_pk_fma_f32 v[24:25], v[22:23], s[66:67], v[10:11] op_sel_hi:[1,0,0]
	v_exp_f32_e32 v26, v26
	v_pk_fma_f32 v[24:25], v[22:23], v[24:25], s[70:71] op_sel_hi:[1,1,0]
	v_exp_f32_e32 v27, v27
	v_pk_fma_f32 v[24:25], v[22:23], v[24:25], s[72:73] op_sel_hi:[1,1,0]
	v_pk_mul_f32 v[16:17], v[16:17], v[0:1] op_sel_hi:[1,0]
	v_pk_fma_f32 v[24:25], v[22:23], v[24:25], s[74:75] op_sel_hi:[1,1,0]
	v_pk_mul_f32 v[12:13], v[12:13], v[0:1] op_sel_hi:[1,0]
	v_pk_mul_f32 v[22:23], v[22:23], v[24:25]
	v_pk_mul_f32 v[24:25], v[16:17], v[16:17]
	v_pk_mul_f32 v[22:23], v[26:27], v[22:23]
	v_pk_mul_f32 v[24:25], v[24:25], s[76:77] op_sel_hi:[1,0]
	v_max_f32_e32 v26, 0, v14
	v_max_f32_e32 v27, 0, v15
	v_fma_f32 v14, -|v14|, v22, v26
	v_fma_f32 v15, -|v15|, v23, v27
	v_exp_f32_e32 v24, v24
	s_nop 0
	s_nop 0
	v_and_b32_e32 v22, 0x7fffffff, v16
	v_exp_f32_e32 v25, v25
	s_nop 0
	v_and_b32_e32 v23, 0x7fffffff, v17
	v_pk_fma_f32 v[22:23], v[22:23], s[64:65], 1.0 op_sel_hi:[1,0,0]
	s_nop 0
	v_rcp_f32_e32 v22, v22
	v_rcp_f32_e32 v23, v23
	v_lshl_add_u64 v[18:19], v[160:161], 1, v[18:19]
	v_pk_mul_f32 v[6:7], v[6:7], v[0:1] op_sel_hi:[1,0]
	v_pk_mul_f32 v[8:9], v[8:9], v[0:1] op_sel_hi:[1,0]
	v_pk_fma_f32 v[26:27], v[22:23], s[66:67], v[10:11] op_sel_hi:[1,0,0]
	v_pk_mul_f32 v[4:5], v[4:5], v[0:1] op_sel_hi:[1,0]
	v_pk_fma_f32 v[26:27], v[22:23], v[26:27], s[70:71] op_sel_hi:[1,1,0]
	s_nop 0
	v_pk_fma_f32 v[26:27], v[22:23], v[26:27], s[72:73] op_sel_hi:[1,1,0]
	s_nop 0
	v_pk_fma_f32 v[26:27], v[22:23], v[26:27], s[74:75] op_sel_hi:[1,1,0]
	s_nop 0
	v_pk_mul_f32 v[22:23], v[22:23], v[26:27]
	v_pk_mul_f32 v[26:27], v[20:21], v[20:21]
	v_pk_mul_f32 v[22:23], v[24:25], v[22:23]
	v_pk_mul_f32 v[26:27], v[26:27], s[76:77] op_sel_hi:[1,0]
	v_max_f32_e32 v24, 0, v16
	v_max_f32_e32 v25, 0, v17
	v_fma_f32 v16, -|v16|, v22, v24
	v_fma_f32 v17, -|v17|, v23, v25
	v_exp_f32_e32 v26, v26
	s_nop 0
	s_nop 0
	v_and_b32_e32 v22, 0x7fffffff, v20
	v_exp_f32_e32 v27, v27
	s_nop 0
	v_and_b32_e32 v23, 0x7fffffff, v21
	v_pk_fma_f32 v[22:23], v[22:23], s[64:65], 1.0 op_sel_hi:[1,0,0]
	s_nop 0
	v_rcp_f32_e32 v22, v22
	v_rcp_f32_e32 v23, v23
	s_nop 0
	v_pk_fma_f32 v[24:25], v[22:23], s[66:67], v[10:11] op_sel_hi:[1,0,0]
	s_nop 0
	v_pk_fma_f32 v[24:25], v[22:23], v[24:25], s[70:71] op_sel_hi:[1,1,0]
	s_nop 0
	v_pk_fma_f32 v[24:25], v[22:23], v[24:25], s[72:73] op_sel_hi:[1,1,0]
	s_nop 0
	v_pk_fma_f32 v[24:25], v[22:23], v[24:25], s[74:75] op_sel_hi:[1,1,0]
	s_nop 0
	v_pk_mul_f32 v[22:23], v[22:23], v[24:25]
	v_pk_mul_f32 v[24:25], v[12:13], v[12:13]
	v_pk_mul_f32 v[22:23], v[26:27], v[22:23]
	v_pk_mul_f32 v[24:25], v[24:25], s[76:77] op_sel_hi:[1,0]
	v_max_f32_e32 v26, 0, v20
	v_max_f32_e32 v27, 0, v21
	v_fma_f32 v20, -|v20|, v22, v26
	v_fma_f32 v21, -|v21|, v23, v27
	v_exp_f32_e32 v24, v24
	s_nop 0
	s_nop 0
	v_and_b32_e32 v22, 0x7fffffff, v12
	v_exp_f32_e32 v25, v25
	s_nop 0
	v_and_b32_e32 v23, 0x7fffffff, v13
	v_pk_fma_f32 v[22:23], v[22:23], s[64:65], 1.0 op_sel_hi:[1,0,0]
	s_nop 0
	v_rcp_f32_e32 v22, v22
	v_rcp_f32_e32 v23, v23
	s_nop 0
	v_pk_fma_f32 v[26:27], v[22:23], s[66:67], v[10:11] op_sel_hi:[1,0,0]
	s_nop 0
	v_pk_fma_f32 v[26:27], v[22:23], v[26:27], s[70:71] op_sel_hi:[1,1,0]
	s_nop 0
	v_pk_fma_f32 v[26:27], v[22:23], v[26:27], s[72:73] op_sel_hi:[1,1,0]
	s_nop 0
	v_pk_fma_f32 v[26:27], v[22:23], v[26:27], s[74:75] op_sel_hi:[1,1,0]
	s_nop 0
	v_pk_mul_f32 v[22:23], v[22:23], v[26:27]
	v_pk_mul_f32 v[26:27], v[6:7], v[6:7]
	v_pk_mul_f32 v[22:23], v[24:25], v[22:23]
	v_pk_mul_f32 v[26:27], v[26:27], s[76:77] op_sel_hi:[1,0]
	v_max_f32_e32 v24, 0, v12
	v_max_f32_e32 v25, 0, v13
	v_fma_f32 v12, -|v12|, v22, v24
	v_fma_f32 v13, -|v13|, v23, v25
	v_exp_f32_e32 v26, v26
	s_nop 0
	s_nop 0
	v_cvt_pk_bf16_f32 v22, v14, v15
	v_exp_f32_e32 v27, v27
	s_nop 0
	s_nop 0
	v_cvt_pk_bf16_f32 v23, v16, v17
	v_cvt_pk_bf16_f32 v24, v20, v21
	v_cvt_pk_bf16_f32 v25, v12, v13
	global_store_dwordx4 v[18:19], v[22:25], off
	s_nop 0
	s_nop 0
	v_pk_mul_f32 v[22:23], v[2:3], v[0:1] op_sel_hi:[1,0]
	v_and_b32_e32 v3, 0x7fffffff, v7
	v_and_b32_e32 v2, 0x7fffffff, v6
	v_pk_fma_f32 v[2:3], v[2:3], s[64:65], 1.0 op_sel_hi:[1,0,0]
	s_nop 0
	v_rcp_f32_e32 v2, v2
	v_rcp_f32_e32 v3, v3
	s_nop 0
	v_pk_fma_f32 v[24:25], v[2:3], s[66:67], v[10:11] op_sel_hi:[1,0,0]
	s_nop 0
	v_pk_fma_f32 v[24:25], v[2:3], v[24:25], s[70:71] op_sel_hi:[1,1,0]
	s_nop 0
	v_pk_fma_f32 v[24:25], v[2:3], v[24:25], s[72:73] op_sel_hi:[1,1,0]
; __device__ __forceinline__ unsigned cvt_pk_bf16(float lo, float hi) { unsigned r; asm volatile("v_cvt_pk_bf16_f32 %0, %1, %2" : "=v"(r) : "v"(lo), "v"(hi)); return r; }
; __device__ __forceinline__ f32x2 gelu_pk(f32x2 v) {
;     const f32x2 av = __builtin_elementwise_abs(v), d = av * 0.2316418882f + 1.0f;
;     f32x2 t; t.x = __builtin_amdgcn_rcpf(d.x); t.y = __builtin_amdgcn_rcpf(d.y);
;     f32x2 q = t * 0.5307027145f + (-0.7265760135f); q = q * t + 0.7107068705f; q = q * t + (-0.142248368f); q = q * t + 0.127414796f; q = q * t;
;     const f32x2 s = (v * v) * (-0.72134752044f);
;     f32x2 e; e.x = __builtin_amdgcn_exp2f(s.x); e.y = __builtin_amdgcn_exp2f(s.y);
;     const f32x2 m = v * (q * e), r = v - m;
;     f32x2 o; o.x = v.x < 0.f ? m.x : r.x; o.y = v.y < 0.f ? m.y : r.y; return o;
; }
;     __device__ __forceinline__ void operator()(const f32x4 (&acc)[2][2][4][2], const Unit& u, int wr, int wc, int fr, int fq) const {
;     ...
;                 for (int bj = 0; bj < 2; ++bj) { f32x4 v0 = acc[ai][bj][m][0] * rs, v1 = acc[ai][bj][m][1] * rs;
;                     const f32x2 a = gelu_pk((f32x2){v0[0], v0[1]}), b = gelu_pk((f32x2){v0[2], v0[3]}), c = gelu_pk((f32x2){v1[0], v1[1]}), d = gelu_pk((f32x2){v1[2], v1[3]});
;                     s1 += ((a.x + a.y) + (b.x + b.y)) + ((c.x + c.y) + (d.x + d.y));
;                     s2 += ((a.x * a.x + a.y * a.y) + (b.x * b.x + b.y * b.y)) + ((c.x * c.x + c.y * c.y) + (d.x * d.x + d.y * d.y));
;                     u32x4 w; w.x = cvt_pk_bf16(a.x, a.y); w.y = cvt_pk_bf16(b.x, b.y); w.z = cvt_pk_bf16(c.x, c.y); w.w = cvt_pk_bf16(d.x, d.y);
;                     *(u32x4*)(rowp + bj * HALF) = w; }
;                 if (isv) { s1 += __shfl_xor(s1, 16); s1 += __shfl_xor(s1, 32); s2 += __shfl_xor(s2, 16); s2 += __shfl_xor(s2, 32);
;                     if (fq == 0) { const int rl = ai * HALF + wr * 64 + m * 16 + fr; part[rl * 4 + wc] = s1; part[1024 + rl * 4 + wc] = s2; } } }
	s_nop 0
	v_pk_fma_f32 v[24:25], v[2:3], v[24:25], s[74:75] op_sel_hi:[1,1,0]
	s_nop 0
	v_pk_mul_f32 v[2:3], v[2:3], v[24:25]
	v_pk_mul_f32 v[24:25], v[8:9], v[8:9]
	v_pk_mul_f32 v[2:3], v[26:27], v[2:3]
	v_pk_mul_f32 v[24:25], v[24:25], s[76:77] op_sel_hi:[1,0]
	v_max_f32_e32 v26, 0, v6
	v_max_f32_e32 v27, 0, v7
	v_fma_f32 v0, -|v6|, v2, v26
	v_fma_f32 v2, -|v7|, v3, v27
	v_and_b32_e32 v6, 0x7fffffff, v8
	s_nop 0
	s_nop 0
	v_and_b32_e32 v7, 0x7fffffff, v9
	v_pk_fma_f32 v[6:7], v[6:7], s[64:65], 1.0 op_sel_hi:[1,0,0]
	s_nop 0
	v_rcp_f32_e32 v6, v6
	v_rcp_f32_e32 v7, v7
	v_exp_f32_e32 v24, v24
	v_exp_f32_e32 v25, v25
	s_nop 0
	v_pk_fma_f32 v[26:27], v[6:7], s[66:67], v[10:11] op_sel_hi:[1,0,0]
	s_nop 0
	v_pk_fma_f32 v[26:27], v[6:7], v[26:27], s[70:71] op_sel_hi:[1,1,0]
	s_nop 0
	v_pk_fma_f32 v[26:27], v[6:7], v[26:27], s[72:73] op_sel_hi:[1,1,0]
	s_nop 0
	v_pk_fma_f32 v[26:27], v[6:7], v[26:27], s[74:75] op_sel_hi:[1,1,0]
	s_nop 0
	v_pk_mul_f32 v[6:7], v[6:7], v[26:27]
	v_pk_mul_f32 v[26:27], v[22:23], v[22:23]
	v_pk_mul_f32 v[6:7], v[24:25], v[6:7]
	v_pk_mul_f32 v[26:27], v[26:27], s[76:77] op_sel_hi:[1,0]
	v_max_f32_e32 v24, 0, v8
	v_max_f32_e32 v25, 0, v9
	v_fma_f32 v3, -|v8|, v6, v24
	v_fma_f32 v6, -|v9|, v7, v25
	v_and_b32_e32 v8, 0x7fffffff, v22
	s_nop 0
	s_nop 0
	v_and_b32_e32 v9, 0x7fffffff, v23
	v_pk_fma_f32 v[8:9], v[8:9], s[64:65], 1.0 op_sel_hi:[1,0,0]
	s_nop 0
	v_rcp_f32_e32 v8, v8
	v_rcp_f32_e32 v9, v9
	v_exp_f32_e32 v26, v26
	v_exp_f32_e32 v27, v27
	s_nop 0
	v_pk_fma_f32 v[24:25], v[8:9], s[66:67], v[10:11] op_sel_hi:[1,0,0]
	s_nop 0
	v_pk_fma_f32 v[24:25], v[8:9], v[24:25], s[70:71] op_sel_hi:[1,1,0]
	s_nop 0
	v_pk_fma_f32 v[24:25], v[8:9], v[24:25], s[72:73] op_sel_hi:[1,1,0]
	s_nop 0
	v_pk_fma_f32 v[24:25], v[8:9], v[24:25], s[74:75] op_sel_hi:[1,1,0]
	s_nop 0
	v_pk_mul_f32 v[8:9], v[8:9], v[24:25]
	v_pk_mul_f32 v[24:25], v[4:5], v[4:5]
	v_pk_mul_f32 v[8:9], v[26:27], v[8:9]
	s_nop 0
	v_max_f32_e32 v26, 0, v22
	v_max_f32_e32 v27, 0, v23
	v_fma_f32 v7, -|v22|, v8, v26
	v_fma_f32 v8, -|v23|, v9, v27
	v_and_b32_e32 v22, 0x7fffffff, v4
	s_nop 0
	s_nop 0
	v_and_b32_e32 v23, 0x7fffffff, v5
	v_pk_fma_f32 v[22:23], v[22:23], s[64:65], 1.0 op_sel_hi:[1,0,0]
	s_nop 0
	v_rcp_f32_e32 v22, v22
	v_rcp_f32_e32 v23, v23
	s_nop 0
	v_pk_fma_f32 v[10:11], v[22:23], s[66:67], v[10:11] op_sel_hi:[1,0,0]
	s_nop 0
	v_pk_fma_f32 v[10:11], v[22:23], v[10:11], s[70:71] op_sel_hi:[1,1,0]
	s_nop 0
	v_pk_fma_f32 v[10:11], v[22:23], v[10:11], s[72:73] op_sel_hi:[1,1,0]
	s_nop 0
	v_pk_fma_f32 v[10:11], v[22:23], v[10:11], s[74:75] op_sel_hi:[1,1,0]
	s_nop 0
	v_pk_mul_f32 v[10:11], v[22:23], v[10:11]
	v_pk_mul_f32 v[22:23], v[24:25], s[76:77] op_sel_hi:[1,0]
	s_nop 0
	v_exp_f32_e32 v22, v22
	v_exp_f32_e32 v23, v23
	s_nop 0
	v_pk_mul_f32 v[10:11], v[22:23], v[10:11]
	s_nop 0
	v_max_f32_e32 v22, 0, v4
	v_max_f32_e32 v23, 0, v5
	v_fma_f32 v4, -|v4|, v10, v22
	v_fma_f32 v5, -|v5|, v11, v23
	s_nop 0
	s_nop 0
	s_nop 0
	v_cvt_pk_bf16_f32 v22, v0, v2
	s_nop 1
	s_nop 0
	s_and_b64 vcc, exec, s[10:11]
	v_cvt_pk_bf16_f32 v23, v3, v6
	v_cvt_pk_bf16_f32 v24, v7, v8
	v_cvt_pk_bf16_f32 v25, v4, v5
	global_store_dwordx4 v[18:19], v[22:25], off offset:256
	s_cbranch_vccnz .LBB0_384
	v_mul_f32_e32 v9, v15, v15
	v_mul_f32_e32 v10, v17, v17
	v_fmac_f32_e32 v9, v14, v14
	v_fmac_f32_e32 v10, v16, v16
	v_add_f32_e32 v9, v9, v10
	v_mul_f32_e32 v10, v21, v21
	v_mul_f32_e32 v11, v13, v13
	v_fmac_f32_e32 v10, v20, v20
	v_fmac_f32_e32 v11, v12, v12
	v_add_f32_e32 v10, v10, v11
	v_add_f32_e32 v9, v9, v10
	v_mul_f32_e32 v10, v2, v2
	v_fmac_f32_e32 v10, v0, v0
	v_mul_f32_e32 v11, v6, v6
	v_add_f32_e32 v0, v0, v2
	v_add_f32_e32 v2, v3, v6
	v_fmac_f32_e32 v11, v3, v3
	v_add_f32_e32 v14, v14, v15
	v_add_f32_e32 v15, v16, v17
	v_add_f32_e32 v0, v0, v2
	v_add_f32_e32 v2, v7, v8
	v_add_f32_e32 v3, v4, v5
	v_add_f32_e32 v14, v14, v15
	v_add_f32_e32 v15, v20, v21
	v_add_f32_e32 v12, v12, v13
	v_add_f32_e32 v2, v2, v3
	v_and_b32_e32 v3, 64, v226
	v_add_f32_e32 v12, v15, v12
	v_add_f32_e32 v0, v0, v2
	v_xor_b32_e32 v2, 16, v226
	v_add_u32_e32 v3, 64, v3
	v_add_f32_e32 v12, v14, v12
	v_cmp_lt_i32_e32 vcc, v2, v3
	v_add_f32_e32 v10, v10, v11
	v_mul_f32_e32 v11, v8, v8
	v_mul_f32_e32 v18, v5, v5
	v_add_f32_e32 v12, 0, v12
	v_cndmask_b32_e32 v2, v226, v2, vcc
	v_fmac_f32_e32 v11, v7, v7
	v_add_f32_e32 v0, v0, v12
	v_lshlrev_b32_e32 v2, 2, v2
	v_fmac_f32_e32 v18, v4, v4
	v_mov_b32_e32 v5, v0
	s_nop 1
	v_permlane16_swap_b32_e32 v5, v0
	v_add_f32_e32 v4, v11, v18
	v_add_f32_e32 v4, v10, v4
	v_add_f32_e32 v4, v9, v4
	v_mov_b32_e32 v6, v4
	s_nop 1
	v_permlane16_swap_b32_e32 v6, v4
	s_waitcnt lgkmcnt(0)
	v_add_f32_e32 v0, v0, v5
	v_xor_b32_e32 v5, 32, v226
	v_cmp_lt_i32_e32 vcc, v5, v3
	v_add_f32_e32 v3, v4, v6
	s_nop 0
	v_cndmask_b32_e32 v2, v226, v5, vcc
	v_lshlrev_b32_e32 v5, 2, v2
	v_mov_b32_e32 v2, v0
	s_nop 1
	v_permlane32_swap_b32_e32 v2, v0
	v_mov_b32_e32 v4, v3
	s_nop 1
	v_permlane32_swap_b32_e32 v4, v3
	s_and_saveexec_b64 s[4:5], s[6:7]
	s_cbranch_execz .LBB0_383
	s_waitcnt lgkmcnt(0)
	v_add_f32_e32 v3, v3, v4
	v_add_f32_e32 v0, v0, v2
	ds_write2st64_b32 v186, v0, v3 offset0:11 offset1:27
